# staging writes vectors v0|v2 and v1|v3 interleaved; scan waves form both dot products with packed f32 ops, no horizontal adds
# speedup vs baseline: 1.0377x; 1.0111x over previous
.LBB0_652:
	ds_read_b128 v[20:23], v6 offset:0
	ds_read_b128 v[28:31], v6 offset:512
	ds_read_b128 v[24:27], v6 offset:256
	ds_read_b128 v[32:35], v6 offset:768
	ds_read_b128 v[56:59], v7 offset:36864
	ds_read_b128 v[36:39], v6 offset:1024
	ds_read_b128 v[40:43], v6 offset:1280
	ds_read2_b32 v[64:65], v8 offset0:0 offset1:16
	ds_read_b128 v[48:51], v6 offset:1792
	ds_read_b128 v[44:47], v6 offset:1536
	ds_read_b128 v[52:55], v6 offset:2048
	ds_read_b128 v[60:63], v7 offset:36880
	s_waitcnt lgkmcnt(11)
	v_pk_mul_f32 v[10:11], v[2:3], v[20:21] op_sel_hi:[0,1]
	ds_read_b128 v[68:71], v6 offset:2304
	s_waitcnt lgkmcnt(10)
	v_pk_mul_f32 v[14:15], v[2:3], v[24:25] op_sel_hi:[0,1]
	v_pk_fma_f32 v[10:11], v[2:3], v[22:23], v[10:11] op_sel:[1,0,0] op_sel_hi:[1,1,1]
	v_pk_fma_f32 v[14:15], v[2:3], v[26:27], v[14:15] op_sel:[1,0,0] op_sel_hi:[1,1,1]
	ds_read_b128 v[76:79], v6 offset:2816
	v_pk_fma_f32 v[10:11], v[4:5], v[28:29], v[10:11] op_sel_hi:[0,1,1]
	s_waitcnt lgkmcnt(10)
	v_pk_fma_f32 v[14:15], v[4:5], v[32:33], v[14:15] op_sel_hi:[0,1,1]
	v_pk_fma_f32 v[10:11], v[4:5], v[30:31], v[10:11] op_sel:[1,0,0] op_sel_hi:[1,1,1]
	ds_read_b128 v[72:75], v6 offset:2560
	v_pk_fma_f32 v[14:15], v[4:5], v[34:35], v[14:15] op_sel:[1,0,0] op_sel_hi:[1,1,1]
	s_waitcnt lgkmcnt(10)
	v_fma_f32 v12, -v56, v10, v11
	s_waitcnt lgkmcnt(9)
	v_pk_mul_f32 v[114:115], v[2:3], v[36:37]
	ds_read_b128 v[80:83], v6 offset:3072
	v_add_f32_dpp v10, v10, v10 row_ror:8 row_mask:0xf bank_mask:0xf bound_ctrl:1
	v_add_f32_dpp v12, v12, v12 row_ror:8 row_mask:0xf bank_mask:0xf bound_ctrl:1
	v_pk_mul_f32 v[116:117], v[4:5], v[38:39]
	ds_read_b128 v[104:107], v7 offset:36912
	v_add_f32_dpp v10, v10, v10 row_ror:4 row_mask:0xf bank_mask:0xf bound_ctrl:1
	v_add_f32_dpp v12, v12, v12 row_ror:4 row_mask:0xf bank_mask:0xf bound_ctrl:1
	s_waitcnt lgkmcnt(9)
	v_pk_fma_f32 v[114:115], v[40:41], v[64:65], v[114:115] op_sel_hi:[1,0,1]
	ds_read_b128 v[84:87], v6 offset:3328
	v_add_f32_dpp v10, v10, v10 row_ror:2 row_mask:0xf bank_mask:0xf bound_ctrl:1
	v_add_f32_dpp v12, v12, v12 row_ror:2 row_mask:0xf bank_mask:0xf bound_ctrl:1
	v_pk_fma_f32 v[116:117], v[42:43], v[64:65], v[116:117] op_sel_hi:[1,0,1]
	ds_read_b128 v[88:91], v6 offset:3584
	v_add_f32_dpp v10, v10, v10 row_ror:1 row_mask:0xf bank_mask:0xf bound_ctrl:1
	v_add_f32_dpp v12, v12, v12 row_ror:1 row_mask:0xf bank_mask:0xf bound_ctrl:1
	v_fmac_f32_e32 v14, v64, v59
	ds_read2_b32 v[112:113], v8 offset0:32 offset1:48
	s_waitcnt lgkmcnt(8)
	v_pk_fma_f32 v[114:115], v[48:49], v[64:65], v[114:115] op_sel:[0,1,0] op_sel_hi:[1,1,1]
	v_fmac_f32_e32 v12, v64, v57
	v_pk_fma_f32 v[116:117], v[50:51], v[64:65], v[116:117] op_sel:[0,1,0] op_sel_hi:[1,1,1]
	ds_read_b128 v[96:99], v6 offset:4096
	v_fmac_f32_e32 v15, v64, v61
	v_pk_fma_f32 v[114:115], v[44:45], v[10:11], v[114:115] op_sel_hi:[1,0,1] neg_lo:[1,0,0] neg_hi:[1,0,0]
	v_fmac_f32_e32 v15, v65, v63
	ds_read_b128 v[92:95], v6 offset:3840
	v_pk_fma_f32 v[116:117], v[46:47], v[10:11], v[116:117] op_sel_hi:[1,0,1] neg_lo:[1,0,0] neg_hi:[1,0,0]
	v_fma_f32 v14, -v10, v58, v14
	v_fma_f32 v15, -v10, v60, v15
	ds_read_b128 v[100:103], v6 offset:4352
	v_fma_f32 v15, -v12, v62, v15
	v_pk_fma_f32 v[2:3], v[52:53], v[12:13], v[114:115] op_sel_hi:[1,0,1] neg_lo:[1,0,0] neg_hi:[1,0,0]
	v_pk_fma_f32 v[4:5], v[54:55], v[12:13], v[116:117] op_sel_hi:[1,0,1] neg_lo:[1,0,0] neg_hi:[1,0,0]
	ds_read_b128 v[108:111], v7 offset:36928
	ds_write2st64_b32 v9, v14, v15 offset0:0 offset1:4
	s_waitcnt lgkmcnt(8)
	v_pk_mul_f32 v[10:11], v[2:3], v[68:69] op_sel_hi:[0,1]
	ds_read_b128 v[20:23], v6 offset:4608
	v_pk_mul_f32 v[14:15], v[2:3], v[72:73] op_sel_hi:[0,1]
	v_pk_fma_f32 v[10:11], v[2:3], v[70:71], v[10:11] op_sel:[1,0,0] op_sel_hi:[1,1,1]
	v_pk_fma_f32 v[14:15], v[2:3], v[74:75], v[14:15] op_sel:[1,0,0] op_sel_hi:[1,1,1]
	ds_read_b128 v[28:31], v6 offset:5120
	v_pk_fma_f32 v[10:11], v[4:5], v[76:77], v[10:11] op_sel_hi:[0,1,1]
	v_pk_fma_f32 v[14:15], v[4:5], v[80:81], v[14:15] op_sel_hi:[0,1,1]
	v_pk_fma_f32 v[10:11], v[4:5], v[78:79], v[10:11] op_sel:[1,0,0] op_sel_hi:[1,1,1]
	ds_read_b128 v[24:27], v6 offset:4864
	v_pk_fma_f32 v[14:15], v[4:5], v[82:83], v[14:15] op_sel:[1,0,0] op_sel_hi:[1,1,1]
	v_fma_f32 v12, -v104, v10, v11
	s_waitcnt lgkmcnt(10)
	v_pk_mul_f32 v[114:115], v[2:3], v[84:85]
	ds_read_b128 v[32:35], v6 offset:5376
	v_add_f32_dpp v10, v10, v10 row_ror:8 row_mask:0xf bank_mask:0xf bound_ctrl:1
	v_add_f32_dpp v12, v12, v12 row_ror:8 row_mask:0xf bank_mask:0xf bound_ctrl:1
	v_pk_mul_f32 v[116:117], v[4:5], v[86:87]
	ds_read_b128 v[56:59], v7 offset:36960
	v_add_f32_dpp v10, v10, v10 row_ror:4 row_mask:0xf bank_mask:0xf bound_ctrl:1
	v_add_f32_dpp v12, v12, v12 row_ror:4 row_mask:0xf bank_mask:0xf bound_ctrl:1
	s_waitcnt lgkmcnt(10)
	v_pk_fma_f32 v[114:115], v[88:89], v[112:113], v[114:115] op_sel_hi:[1,0,1]
	ds_read_b128 v[36:39], v6 offset:5632
	v_add_f32_dpp v10, v10, v10 row_ror:2 row_mask:0xf bank_mask:0xf bound_ctrl:1
	v_add_f32_dpp v12, v12, v12 row_ror:2 row_mask:0xf bank_mask:0xf bound_ctrl:1
	v_pk_fma_f32 v[116:117], v[90:91], v[112:113], v[116:117] op_sel_hi:[1,0,1]
	ds_read_b128 v[40:43], v6 offset:5888
	v_add_f32_dpp v10, v10, v10 row_ror:1 row_mask:0xf bank_mask:0xf bound_ctrl:1
	v_add_f32_dpp v12, v12, v12 row_ror:1 row_mask:0xf bank_mask:0xf bound_ctrl:1
	v_fmac_f32_e32 v14, v112, v107
	ds_read2_b32 v[64:65], v8 offset0:64 offset1:80
	s_waitcnt lgkmcnt(9)
	v_pk_fma_f32 v[114:115], v[96:97], v[112:113], v[114:115] op_sel:[0,1,0] op_sel_hi:[1,1,1]
	v_fmac_f32_e32 v12, v112, v105
	v_pk_fma_f32 v[116:117], v[98:99], v[112:113], v[116:117] op_sel:[0,1,0] op_sel_hi:[1,1,1]
	ds_read_b128 v[48:51], v6 offset:6400
	v_fmac_f32_e32 v15, v112, v109
	v_pk_fma_f32 v[114:115], v[92:93], v[10:11], v[114:115] op_sel_hi:[1,0,1] neg_lo:[1,0,0] neg_hi:[1,0,0]
	v_fmac_f32_e32 v15, v113, v111
	ds_read_b128 v[44:47], v6 offset:6144
	v_pk_fma_f32 v[116:117], v[94:95], v[10:11], v[116:117] op_sel_hi:[1,0,1] neg_lo:[1,0,0] neg_hi:[1,0,0]
	v_fma_f32 v14, -v10, v106, v14
	v_fma_f32 v15, -v10, v108, v15
	ds_read_b128 v[52:55], v6 offset:6656
	v_fma_f32 v15, -v12, v110, v15
	v_pk_fma_f32 v[2:3], v[100:101], v[12:13], v[114:115] op_sel_hi:[1,0,1] neg_lo:[1,0,0] neg_hi:[1,0,0]
	v_pk_fma_f32 v[4:5], v[102:103], v[12:13], v[116:117] op_sel_hi:[1,0,1] neg_lo:[1,0,0] neg_hi:[1,0,0]
	ds_read_b128 v[60:63], v7 offset:36976
	ds_write2st64_b32 v9, v14, v15 offset0:8 offset1:12
	s_waitcnt lgkmcnt(8)
	v_pk_mul_f32 v[10:11], v[2:3], v[20:21] op_sel_hi:[0,1]
	ds_read_b128 v[68:71], v6 offset:6912
	v_pk_mul_f32 v[14:15], v[2:3], v[24:25] op_sel_hi:[0,1]
	v_pk_fma_f32 v[10:11], v[2:3], v[22:23], v[10:11] op_sel:[1,0,0] op_sel_hi:[1,1,1]
	v_pk_fma_f32 v[14:15], v[2:3], v[26:27], v[14:15] op_sel:[1,0,0] op_sel_hi:[1,1,1]
	ds_read_b128 v[76:79], v6 offset:7424
	v_pk_fma_f32 v[10:11], v[4:5], v[28:29], v[10:11] op_sel_hi:[0,1,1]
	v_pk_fma_f32 v[14:15], v[4:5], v[32:33], v[14:15] op_sel_hi:[0,1,1]
	v_pk_fma_f32 v[10:11], v[4:5], v[30:31], v[10:11] op_sel:[1,0,0] op_sel_hi:[1,1,1]
	ds_read_b128 v[72:75], v6 offset:7168
	v_pk_fma_f32 v[14:15], v[4:5], v[34:35], v[14:15] op_sel:[1,0,0] op_sel_hi:[1,1,1]
	v_fma_f32 v12, -v56, v10, v11
	s_waitcnt lgkmcnt(10)
	v_pk_mul_f32 v[114:115], v[2:3], v[36:37]
	ds_read_b128 v[80:83], v6 offset:7680
	v_add_f32_dpp v10, v10, v10 row_ror:8 row_mask:0xf bank_mask:0xf bound_ctrl:1
	v_add_f32_dpp v12, v12, v12 row_ror:8 row_mask:0xf bank_mask:0xf bound_ctrl:1
	v_pk_mul_f32 v[116:117], v[4:5], v[38:39]
	ds_read_b128 v[104:107], v7 offset:37008
	v_add_f32_dpp v10, v10, v10 row_ror:4 row_mask:0xf bank_mask:0xf bound_ctrl:1
	v_add_f32_dpp v12, v12, v12 row_ror:4 row_mask:0xf bank_mask:0xf bound_ctrl:1
	s_waitcnt lgkmcnt(10)
	v_pk_fma_f32 v[114:115], v[40:41], v[64:65], v[114:115] op_sel_hi:[1,0,1]
	ds_read_b128 v[84:87], v6 offset:7936
	v_add_f32_dpp v10, v10, v10 row_ror:2 row_mask:0xf bank_mask:0xf bound_ctrl:1
	v_add_f32_dpp v12, v12, v12 row_ror:2 row_mask:0xf bank_mask:0xf bound_ctrl:1
	v_pk_fma_f32 v[116:117], v[42:43], v[64:65], v[116:117] op_sel_hi:[1,0,1]
	ds_read_b128 v[88:91], v6 offset:8192
	v_add_f32_dpp v10, v10, v10 row_ror:1 row_mask:0xf bank_mask:0xf bound_ctrl:1
	v_add_f32_dpp v12, v12, v12 row_ror:1 row_mask:0xf bank_mask:0xf bound_ctrl:1
	v_fmac_f32_e32 v14, v64, v59
	ds_read2_b32 v[112:113], v8 offset0:96 offset1:112
	s_waitcnt lgkmcnt(9)
	v_pk_fma_f32 v[114:115], v[48:49], v[64:65], v[114:115] op_sel:[0,1,0] op_sel_hi:[1,1,1]
	v_fmac_f32_e32 v12, v64, v57
	v_pk_fma_f32 v[116:117], v[50:51], v[64:65], v[116:117] op_sel:[0,1,0] op_sel_hi:[1,1,1]
	ds_read_b128 v[96:99], v6 offset:8704
	v_fmac_f32_e32 v15, v64, v61
	v_pk_fma_f32 v[114:115], v[44:45], v[10:11], v[114:115] op_sel_hi:[1,0,1] neg_lo:[1,0,0] neg_hi:[1,0,0]
	v_fmac_f32_e32 v15, v65, v63
	ds_read_b128 v[92:95], v6 offset:8448
	v_pk_fma_f32 v[116:117], v[46:47], v[10:11], v[116:117] op_sel_hi:[1,0,1] neg_lo:[1,0,0] neg_hi:[1,0,0]
	v_fma_f32 v14, -v10, v58, v14
	v_fma_f32 v15, -v10, v60, v15
	ds_read_b128 v[100:103], v6 offset:8960
	v_fma_f32 v15, -v12, v62, v15
	v_pk_fma_f32 v[2:3], v[52:53], v[12:13], v[114:115] op_sel_hi:[1,0,1] neg_lo:[1,0,0] neg_hi:[1,0,0]
	v_pk_fma_f32 v[4:5], v[54:55], v[12:13], v[116:117] op_sel_hi:[1,0,1] neg_lo:[1,0,0] neg_hi:[1,0,0]
	ds_read_b128 v[108:111], v7 offset:37024
	ds_write2st64_b32 v9, v14, v15 offset0:16 offset1:20
	s_waitcnt lgkmcnt(8)
	v_pk_mul_f32 v[10:11], v[2:3], v[68:69] op_sel_hi:[0,1]
	ds_read_b128 v[20:23], v6 offset:9216
	v_pk_mul_f32 v[14:15], v[2:3], v[72:73] op_sel_hi:[0,1]
	v_pk_fma_f32 v[10:11], v[2:3], v[70:71], v[10:11] op_sel:[1,0,0] op_sel_hi:[1,1,1]
	v_pk_fma_f32 v[14:15], v[2:3], v[74:75], v[14:15] op_sel:[1,0,0] op_sel_hi:[1,1,1]
	ds_read_b128 v[28:31], v6 offset:9728
	v_pk_fma_f32 v[10:11], v[4:5], v[76:77], v[10:11] op_sel_hi:[0,1,1]
	v_pk_fma_f32 v[14:15], v[4:5], v[80:81], v[14:15] op_sel_hi:[0,1,1]
	v_pk_fma_f32 v[10:11], v[4:5], v[78:79], v[10:11] op_sel:[1,0,0] op_sel_hi:[1,1,1]
	ds_read_b128 v[24:27], v6 offset:9472
	v_pk_fma_f32 v[14:15], v[4:5], v[82:83], v[14:15] op_sel:[1,0,0] op_sel_hi:[1,1,1]
	v_fma_f32 v12, -v104, v10, v11
	s_waitcnt lgkmcnt(10)
	v_pk_mul_f32 v[114:115], v[2:3], v[84:85]
	ds_read_b128 v[32:35], v6 offset:9984
	v_add_f32_dpp v10, v10, v10 row_ror:8 row_mask:0xf bank_mask:0xf bound_ctrl:1
	v_add_f32_dpp v12, v12, v12 row_ror:8 row_mask:0xf bank_mask:0xf bound_ctrl:1
	v_pk_mul_f32 v[116:117], v[4:5], v[86:87]
	ds_read_b128 v[56:59], v7 offset:37056
	v_add_f32_dpp v10, v10, v10 row_ror:4 row_mask:0xf bank_mask:0xf bound_ctrl:1
	v_add_f32_dpp v12, v12, v12 row_ror:4 row_mask:0xf bank_mask:0xf bound_ctrl:1
	s_waitcnt lgkmcnt(10)
	v_pk_fma_f32 v[114:115], v[88:89], v[112:113], v[114:115] op_sel_hi:[1,0,1]
	ds_read_b128 v[36:39], v6 offset:10240
	v_add_f32_dpp v10, v10, v10 row_ror:2 row_mask:0xf bank_mask:0xf bound_ctrl:1
	v_add_f32_dpp v12, v12, v12 row_ror:2 row_mask:0xf bank_mask:0xf bound_ctrl:1
	v_pk_fma_f32 v[116:117], v[90:91], v[112:113], v[116:117] op_sel_hi:[1,0,1]
	ds_read_b128 v[40:43], v6 offset:10496
	v_add_f32_dpp v10, v10, v10 row_ror:1 row_mask:0xf bank_mask:0xf bound_ctrl:1
	v_add_f32_dpp v12, v12, v12 row_ror:1 row_mask:0xf bank_mask:0xf bound_ctrl:1
	v_fmac_f32_e32 v14, v112, v107
	ds_read2_b32 v[64:65], v8 offset0:128 offset1:144
	s_waitcnt lgkmcnt(9)
	v_pk_fma_f32 v[114:115], v[96:97], v[112:113], v[114:115] op_sel:[0,1,0] op_sel_hi:[1,1,1]
	v_fmac_f32_e32 v12, v112, v105
	v_pk_fma_f32 v[116:117], v[98:99], v[112:113], v[116:117] op_sel:[0,1,0] op_sel_hi:[1,1,1]
	ds_read_b128 v[48:51], v6 offset:11008
	v_fmac_f32_e32 v15, v112, v109
	v_pk_fma_f32 v[114:115], v[92:93], v[10:11], v[114:115] op_sel_hi:[1,0,1] neg_lo:[1,0,0] neg_hi:[1,0,0]
	v_fmac_f32_e32 v15, v113, v111
	ds_read_b128 v[44:47], v6 offset:10752
	v_pk_fma_f32 v[116:117], v[94:95], v[10:11], v[116:117] op_sel_hi:[1,0,1] neg_lo:[1,0,0] neg_hi:[1,0,0]
	v_fma_f32 v14, -v10, v106, v14
	v_fma_f32 v15, -v10, v108, v15
	ds_read_b128 v[52:55], v6 offset:11264
	v_fma_f32 v15, -v12, v110, v15
	v_pk_fma_f32 v[2:3], v[100:101], v[12:13], v[114:115] op_sel_hi:[1,0,1] neg_lo:[1,0,0] neg_hi:[1,0,0]
	v_pk_fma_f32 v[4:5], v[102:103], v[12:13], v[116:117] op_sel_hi:[1,0,1] neg_lo:[1,0,0] neg_hi:[1,0,0]
	ds_read_b128 v[60:63], v7 offset:37072
	ds_write2st64_b32 v9, v14, v15 offset0:24 offset1:28
	s_waitcnt lgkmcnt(8)
	v_pk_mul_f32 v[10:11], v[2:3], v[20:21] op_sel_hi:[0,1]
	ds_read_b128 v[68:71], v6 offset:11520
	v_pk_mul_f32 v[14:15], v[2:3], v[24:25] op_sel_hi:[0,1]
	v_pk_fma_f32 v[10:11], v[2:3], v[22:23], v[10:11] op_sel:[1,0,0] op_sel_hi:[1,1,1]
	v_pk_fma_f32 v[14:15], v[2:3], v[26:27], v[14:15] op_sel:[1,0,0] op_sel_hi:[1,1,1]
	ds_read_b128 v[76:79], v6 offset:12032
	v_pk_fma_f32 v[10:11], v[4:5], v[28:29], v[10:11] op_sel_hi:[0,1,1]
	v_pk_fma_f32 v[14:15], v[4:5], v[32:33], v[14:15] op_sel_hi:[0,1,1]
	v_pk_fma_f32 v[10:11], v[4:5], v[30:31], v[10:11] op_sel:[1,0,0] op_sel_hi:[1,1,1]
	ds_read_b128 v[72:75], v6 offset:11776
	v_pk_fma_f32 v[14:15], v[4:5], v[34:35], v[14:15] op_sel:[1,0,0] op_sel_hi:[1,1,1]
	v_fma_f32 v12, -v56, v10, v11
	s_waitcnt lgkmcnt(10)
	v_pk_mul_f32 v[114:115], v[2:3], v[36:37]
	ds_read_b128 v[80:83], v6 offset:12288
	v_add_f32_dpp v10, v10, v10 row_ror:8 row_mask:0xf bank_mask:0xf bound_ctrl:1
	v_add_f32_dpp v12, v12, v12 row_ror:8 row_mask:0xf bank_mask:0xf bound_ctrl:1
	v_pk_mul_f32 v[116:117], v[4:5], v[38:39]
	ds_read_b128 v[104:107], v7 offset:37104
	v_add_f32_dpp v10, v10, v10 row_ror:4 row_mask:0xf bank_mask:0xf bound_ctrl:1
	v_add_f32_dpp v12, v12, v12 row_ror:4 row_mask:0xf bank_mask:0xf bound_ctrl:1
	s_waitcnt lgkmcnt(10)
	v_pk_fma_f32 v[114:115], v[40:41], v[64:65], v[114:115] op_sel_hi:[1,0,1]
	ds_read_b128 v[84:87], v6 offset:12544
	v_add_f32_dpp v10, v10, v10 row_ror:2 row_mask:0xf bank_mask:0xf bound_ctrl:1
	v_add_f32_dpp v12, v12, v12 row_ror:2 row_mask:0xf bank_mask:0xf bound_ctrl:1
	v_pk_fma_f32 v[116:117], v[42:43], v[64:65], v[116:117] op_sel_hi:[1,0,1]
	ds_read_b128 v[88:91], v6 offset:12800
	v_add_f32_dpp v10, v10, v10 row_ror:1 row_mask:0xf bank_mask:0xf bound_ctrl:1
	v_add_f32_dpp v12, v12, v12 row_ror:1 row_mask:0xf bank_mask:0xf bound_ctrl:1
	v_fmac_f32_e32 v14, v64, v59
	ds_read2_b32 v[112:113], v8 offset0:160 offset1:176
	s_waitcnt lgkmcnt(9)
	v_pk_fma_f32 v[114:115], v[48:49], v[64:65], v[114:115] op_sel:[0,1,0] op_sel_hi:[1,1,1]
	v_fmac_f32_e32 v12, v64, v57
	v_pk_fma_f32 v[116:117], v[50:51], v[64:65], v[116:117] op_sel:[0,1,0] op_sel_hi:[1,1,1]
	ds_read_b128 v[96:99], v6 offset:13312
	v_fmac_f32_e32 v15, v64, v61
	v_pk_fma_f32 v[114:115], v[44:45], v[10:11], v[114:115] op_sel_hi:[1,0,1] neg_lo:[1,0,0] neg_hi:[1,0,0]
	v_fmac_f32_e32 v15, v65, v63
	ds_read_b128 v[92:95], v6 offset:13056
	v_pk_fma_f32 v[116:117], v[46:47], v[10:11], v[116:117] op_sel_hi:[1,0,1] neg_lo:[1,0,0] neg_hi:[1,0,0]
	v_fma_f32 v14, -v10, v58, v14
	v_fma_f32 v15, -v10, v60, v15
	ds_read_b128 v[100:103], v6 offset:13568
	v_fma_f32 v15, -v12, v62, v15
	v_pk_fma_f32 v[2:3], v[52:53], v[12:13], v[114:115] op_sel_hi:[1,0,1] neg_lo:[1,0,0] neg_hi:[1,0,0]
	v_pk_fma_f32 v[4:5], v[54:55], v[12:13], v[116:117] op_sel_hi:[1,0,1] neg_lo:[1,0,0] neg_hi:[1,0,0]
	ds_read_b128 v[108:111], v7 offset:37120
	ds_write2st64_b32 v9, v14, v15 offset0:32 offset1:36
	s_waitcnt lgkmcnt(8)
	v_pk_mul_f32 v[10:11], v[2:3], v[68:69] op_sel_hi:[0,1]
	ds_read_b128 v[20:23], v6 offset:13824
	v_pk_mul_f32 v[14:15], v[2:3], v[72:73] op_sel_hi:[0,1]
	v_pk_fma_f32 v[10:11], v[2:3], v[70:71], v[10:11] op_sel:[1,0,0] op_sel_hi:[1,1,1]
	v_pk_fma_f32 v[14:15], v[2:3], v[74:75], v[14:15] op_sel:[1,0,0] op_sel_hi:[1,1,1]
	ds_read_b128 v[28:31], v6 offset:14336
	v_pk_fma_f32 v[10:11], v[4:5], v[76:77], v[10:11] op_sel_hi:[0,1,1]
	v_pk_fma_f32 v[14:15], v[4:5], v[80:81], v[14:15] op_sel_hi:[0,1,1]
	v_pk_fma_f32 v[10:11], v[4:5], v[78:79], v[10:11] op_sel:[1,0,0] op_sel_hi:[1,1,1]
	ds_read_b128 v[24:27], v6 offset:14080
	v_pk_fma_f32 v[14:15], v[4:5], v[82:83], v[14:15] op_sel:[1,0,0] op_sel_hi:[1,1,1]
	v_fma_f32 v12, -v104, v10, v11
	s_waitcnt lgkmcnt(10)
	v_pk_mul_f32 v[114:115], v[2:3], v[84:85]
	ds_read_b128 v[32:35], v6 offset:14592
	v_add_f32_dpp v10, v10, v10 row_ror:8 row_mask:0xf bank_mask:0xf bound_ctrl:1
	v_add_f32_dpp v12, v12, v12 row_ror:8 row_mask:0xf bank_mask:0xf bound_ctrl:1
	v_pk_mul_f32 v[116:117], v[4:5], v[86:87]
	ds_read_b128 v[56:59], v7 offset:37152
	v_add_f32_dpp v10, v10, v10 row_ror:4 row_mask:0xf bank_mask:0xf bound_ctrl:1
	v_add_f32_dpp v12, v12, v12 row_ror:4 row_mask:0xf bank_mask:0xf bound_ctrl:1
	s_waitcnt lgkmcnt(10)
	v_pk_fma_f32 v[114:115], v[88:89], v[112:113], v[114:115] op_sel_hi:[1,0,1]
	ds_read_b128 v[36:39], v6 offset:14848
	v_add_f32_dpp v10, v10, v10 row_ror:2 row_mask:0xf bank_mask:0xf bound_ctrl:1
	v_add_f32_dpp v12, v12, v12 row_ror:2 row_mask:0xf bank_mask:0xf bound_ctrl:1
	v_pk_fma_f32 v[116:117], v[90:91], v[112:113], v[116:117] op_sel_hi:[1,0,1]
	ds_read_b128 v[40:43], v6 offset:15104
	v_add_f32_dpp v10, v10, v10 row_ror:1 row_mask:0xf bank_mask:0xf bound_ctrl:1
	v_add_f32_dpp v12, v12, v12 row_ror:1 row_mask:0xf bank_mask:0xf bound_ctrl:1
	v_fmac_f32_e32 v14, v112, v107
	ds_read2_b32 v[64:65], v8 offset0:192 offset1:208
	s_waitcnt lgkmcnt(9)
	v_pk_fma_f32 v[114:115], v[96:97], v[112:113], v[114:115] op_sel:[0,1,0] op_sel_hi:[1,1,1]
	v_fmac_f32_e32 v12, v112, v105
	v_pk_fma_f32 v[116:117], v[98:99], v[112:113], v[116:117] op_sel:[0,1,0] op_sel_hi:[1,1,1]
	ds_read_b128 v[48:51], v6 offset:15616
	v_fmac_f32_e32 v15, v112, v109
	v_pk_fma_f32 v[114:115], v[92:93], v[10:11], v[114:115] op_sel_hi:[1,0,1] neg_lo:[1,0,0] neg_hi:[1,0,0]
	v_fmac_f32_e32 v15, v113, v111
	ds_read_b128 v[44:47], v6 offset:15360
	v_pk_fma_f32 v[116:117], v[94:95], v[10:11], v[116:117] op_sel_hi:[1,0,1] neg_lo:[1,0,0] neg_hi:[1,0,0]
	v_fma_f32 v14, -v10, v106, v14
	v_fma_f32 v15, -v10, v108, v15
	ds_read_b128 v[52:55], v6 offset:15872
	v_fma_f32 v15, -v12, v110, v15
	v_pk_fma_f32 v[2:3], v[100:101], v[12:13], v[114:115] op_sel_hi:[1,0,1] neg_lo:[1,0,0] neg_hi:[1,0,0]
	v_pk_fma_f32 v[4:5], v[102:103], v[12:13], v[116:117] op_sel_hi:[1,0,1] neg_lo:[1,0,0] neg_hi:[1,0,0]
	ds_read_b128 v[60:63], v7 offset:37168
	ds_write2st64_b32 v9, v14, v15 offset0:40 offset1:44
	s_waitcnt lgkmcnt(8)
	v_pk_mul_f32 v[10:11], v[2:3], v[20:21] op_sel_hi:[0,1]
	ds_read_b128 v[68:71], v6 offset:16128
	v_pk_mul_f32 v[14:15], v[2:3], v[24:25] op_sel_hi:[0,1]
	v_pk_fma_f32 v[10:11], v[2:3], v[22:23], v[10:11] op_sel:[1,0,0] op_sel_hi:[1,1,1]
	v_pk_fma_f32 v[14:15], v[2:3], v[26:27], v[14:15] op_sel:[1,0,0] op_sel_hi:[1,1,1]
	ds_read_b128 v[76:79], v6 offset:16640
	v_pk_fma_f32 v[10:11], v[4:5], v[28:29], v[10:11] op_sel_hi:[0,1,1]
	v_pk_fma_f32 v[14:15], v[4:5], v[32:33], v[14:15] op_sel_hi:[0,1,1]
	v_pk_fma_f32 v[10:11], v[4:5], v[30:31], v[10:11] op_sel:[1,0,0] op_sel_hi:[1,1,1]
	ds_read_b128 v[72:75], v6 offset:16384
	v_pk_fma_f32 v[14:15], v[4:5], v[34:35], v[14:15] op_sel:[1,0,0] op_sel_hi:[1,1,1]
	v_fma_f32 v12, -v56, v10, v11
	s_waitcnt lgkmcnt(10)
	v_pk_mul_f32 v[114:115], v[2:3], v[36:37]
	ds_read_b128 v[80:83], v6 offset:16896
	v_add_f32_dpp v10, v10, v10 row_ror:8 row_mask:0xf bank_mask:0xf bound_ctrl:1
	v_add_f32_dpp v12, v12, v12 row_ror:8 row_mask:0xf bank_mask:0xf bound_ctrl:1
	v_pk_mul_f32 v[116:117], v[4:5], v[38:39]
	ds_read_b128 v[104:107], v7 offset:37200
	v_add_f32_dpp v10, v10, v10 row_ror:4 row_mask:0xf bank_mask:0xf bound_ctrl:1
	v_add_f32_dpp v12, v12, v12 row_ror:4 row_mask:0xf bank_mask:0xf bound_ctrl:1
	s_waitcnt lgkmcnt(10)
	v_pk_fma_f32 v[114:115], v[40:41], v[64:65], v[114:115] op_sel_hi:[1,0,1]
	ds_read_b128 v[84:87], v6 offset:17152
	v_add_f32_dpp v10, v10, v10 row_ror:2 row_mask:0xf bank_mask:0xf bound_ctrl:1
	v_add_f32_dpp v12, v12, v12 row_ror:2 row_mask:0xf bank_mask:0xf bound_ctrl:1
	v_pk_fma_f32 v[116:117], v[42:43], v[64:65], v[116:117] op_sel_hi:[1,0,1]
	ds_read_b128 v[88:91], v6 offset:17408
	v_add_f32_dpp v10, v10, v10 row_ror:1 row_mask:0xf bank_mask:0xf bound_ctrl:1
	v_add_f32_dpp v12, v12, v12 row_ror:1 row_mask:0xf bank_mask:0xf bound_ctrl:1
	v_fmac_f32_e32 v14, v64, v59
	ds_read2_b32 v[112:113], v8 offset0:224 offset1:240
	s_waitcnt lgkmcnt(9)
	v_pk_fma_f32 v[114:115], v[48:49], v[64:65], v[114:115] op_sel:[0,1,0] op_sel_hi:[1,1,1]
	v_fmac_f32_e32 v12, v64, v57
	v_pk_fma_f32 v[116:117], v[50:51], v[64:65], v[116:117] op_sel:[0,1,0] op_sel_hi:[1,1,1]
	ds_read_b128 v[96:99], v6 offset:17920
	v_fmac_f32_e32 v15, v64, v61
	v_pk_fma_f32 v[114:115], v[44:45], v[10:11], v[114:115] op_sel_hi:[1,0,1] neg_lo:[1,0,0] neg_hi:[1,0,0]
	v_fmac_f32_e32 v15, v65, v63
	ds_read_b128 v[92:95], v6 offset:17664
	v_pk_fma_f32 v[116:117], v[46:47], v[10:11], v[116:117] op_sel_hi:[1,0,1] neg_lo:[1,0,0] neg_hi:[1,0,0]
	v_fma_f32 v14, -v10, v58, v14
	v_fma_f32 v15, -v10, v60, v15
	ds_read_b128 v[100:103], v6 offset:18176
	v_fma_f32 v15, -v12, v62, v15
	v_pk_fma_f32 v[2:3], v[52:53], v[12:13], v[114:115] op_sel_hi:[1,0,1] neg_lo:[1,0,0] neg_hi:[1,0,0]
	v_pk_fma_f32 v[4:5], v[54:55], v[12:13], v[116:117] op_sel_hi:[1,0,1] neg_lo:[1,0,0] neg_hi:[1,0,0]
	ds_read_b128 v[108:111], v7 offset:37216
	ds_write2st64_b32 v9, v14, v15 offset0:48 offset1:52
	s_waitcnt lgkmcnt(8)
	v_pk_mul_f32 v[10:11], v[2:3], v[68:69] op_sel_hi:[0,1]
	ds_read_b128 v[20:23], v6 offset:18432
	v_pk_mul_f32 v[14:15], v[2:3], v[72:73] op_sel_hi:[0,1]
	v_pk_fma_f32 v[10:11], v[2:3], v[70:71], v[10:11] op_sel:[1,0,0] op_sel_hi:[1,1,1]
	v_pk_fma_f32 v[14:15], v[2:3], v[74:75], v[14:15] op_sel:[1,0,0] op_sel_hi:[1,1,1]
	ds_read_b128 v[28:31], v6 offset:18944
	v_pk_fma_f32 v[10:11], v[4:5], v[76:77], v[10:11] op_sel_hi:[0,1,1]
	v_pk_fma_f32 v[14:15], v[4:5], v[80:81], v[14:15] op_sel_hi:[0,1,1]
	v_pk_fma_f32 v[10:11], v[4:5], v[78:79], v[10:11] op_sel:[1,0,0] op_sel_hi:[1,1,1]
	ds_read_b128 v[24:27], v6 offset:18688
	v_pk_fma_f32 v[14:15], v[4:5], v[82:83], v[14:15] op_sel:[1,0,0] op_sel_hi:[1,1,1]
	v_fma_f32 v12, -v104, v10, v11
	s_waitcnt lgkmcnt(10)
	v_pk_mul_f32 v[114:115], v[2:3], v[84:85]
	ds_read_b128 v[32:35], v6 offset:19200
	v_add_f32_dpp v10, v10, v10 row_ror:8 row_mask:0xf bank_mask:0xf bound_ctrl:1
	v_add_f32_dpp v12, v12, v12 row_ror:8 row_mask:0xf bank_mask:0xf bound_ctrl:1
	v_pk_mul_f32 v[116:117], v[4:5], v[86:87]
	ds_read_b128 v[56:59], v7 offset:37248
	v_add_f32_dpp v10, v10, v10 row_ror:4 row_mask:0xf bank_mask:0xf bound_ctrl:1
	v_add_f32_dpp v12, v12, v12 row_ror:4 row_mask:0xf bank_mask:0xf bound_ctrl:1
	s_waitcnt lgkmcnt(10)
	v_pk_fma_f32 v[114:115], v[88:89], v[112:113], v[114:115] op_sel_hi:[1,0,1]
	ds_read_b128 v[36:39], v6 offset:19456
	v_add_f32_dpp v10, v10, v10 row_ror:2 row_mask:0xf bank_mask:0xf bound_ctrl:1
	v_add_f32_dpp v12, v12, v12 row_ror:2 row_mask:0xf bank_mask:0xf bound_ctrl:1
	v_pk_fma_f32 v[116:117], v[90:91], v[112:113], v[116:117] op_sel_hi:[1,0,1]
	ds_read_b128 v[40:43], v6 offset:19712
	v_add_f32_dpp v10, v10, v10 row_ror:1 row_mask:0xf bank_mask:0xf bound_ctrl:1
	v_add_f32_dpp v12, v12, v12 row_ror:1 row_mask:0xf bank_mask:0xf bound_ctrl:1
	v_fmac_f32_e32 v14, v112, v107
	ds_read2_b32 v[64:65], v120 offset0:0 offset1:16
	s_waitcnt lgkmcnt(9)
	v_pk_fma_f32 v[114:115], v[96:97], v[112:113], v[114:115] op_sel:[0,1,0] op_sel_hi:[1,1,1]
	v_fmac_f32_e32 v12, v112, v105
	v_pk_fma_f32 v[116:117], v[98:99], v[112:113], v[116:117] op_sel:[0,1,0] op_sel_hi:[1,1,1]
	ds_read_b128 v[48:51], v6 offset:20224
	v_fmac_f32_e32 v15, v112, v109
	v_pk_fma_f32 v[114:115], v[92:93], v[10:11], v[114:115] op_sel_hi:[1,0,1] neg_lo:[1,0,0] neg_hi:[1,0,0]
	v_fmac_f32_e32 v15, v113, v111
	ds_read_b128 v[44:47], v6 offset:19968
	v_pk_fma_f32 v[116:117], v[94:95], v[10:11], v[116:117] op_sel_hi:[1,0,1] neg_lo:[1,0,0] neg_hi:[1,0,0]
	v_fma_f32 v14, -v10, v106, v14
	v_fma_f32 v15, -v10, v108, v15
	ds_read_b128 v[52:55], v6 offset:20480
	v_fma_f32 v15, -v12, v110, v15
	v_pk_fma_f32 v[2:3], v[100:101], v[12:13], v[114:115] op_sel_hi:[1,0,1] neg_lo:[1,0,0] neg_hi:[1,0,0]
	v_pk_fma_f32 v[4:5], v[102:103], v[12:13], v[116:117] op_sel_hi:[1,0,1] neg_lo:[1,0,0] neg_hi:[1,0,0]
	ds_read_b128 v[60:63], v7 offset:37264
	ds_write2st64_b32 v9, v14, v15 offset0:56 offset1:60
	s_waitcnt lgkmcnt(8)
	v_pk_mul_f32 v[10:11], v[2:3], v[20:21] op_sel_hi:[0,1]
	ds_read_b128 v[68:71], v6 offset:20736
	v_pk_mul_f32 v[14:15], v[2:3], v[24:25] op_sel_hi:[0,1]
	v_pk_fma_f32 v[10:11], v[2:3], v[22:23], v[10:11] op_sel:[1,0,0] op_sel_hi:[1,1,1]
	v_pk_fma_f32 v[14:15], v[2:3], v[26:27], v[14:15] op_sel:[1,0,0] op_sel_hi:[1,1,1]
	ds_read_b128 v[76:79], v6 offset:21248
	v_pk_fma_f32 v[10:11], v[4:5], v[28:29], v[10:11] op_sel_hi:[0,1,1]
	v_pk_fma_f32 v[14:15], v[4:5], v[32:33], v[14:15] op_sel_hi:[0,1,1]
	v_pk_fma_f32 v[10:11], v[4:5], v[30:31], v[10:11] op_sel:[1,0,0] op_sel_hi:[1,1,1]
	ds_read_b128 v[72:75], v6 offset:20992
	v_pk_fma_f32 v[14:15], v[4:5], v[34:35], v[14:15] op_sel:[1,0,0] op_sel_hi:[1,1,1]
	v_fma_f32 v12, -v56, v10, v11
	s_waitcnt lgkmcnt(10)
	v_pk_mul_f32 v[114:115], v[2:3], v[36:37]
	ds_read_b128 v[80:83], v6 offset:21504
	v_add_f32_dpp v10, v10, v10 row_ror:8 row_mask:0xf bank_mask:0xf bound_ctrl:1
	v_add_f32_dpp v12, v12, v12 row_ror:8 row_mask:0xf bank_mask:0xf bound_ctrl:1
	v_pk_mul_f32 v[116:117], v[4:5], v[38:39]
	ds_read_b128 v[104:107], v7 offset:37296
	v_add_f32_dpp v10, v10, v10 row_ror:4 row_mask:0xf bank_mask:0xf bound_ctrl:1
	v_add_f32_dpp v12, v12, v12 row_ror:4 row_mask:0xf bank_mask:0xf bound_ctrl:1
	s_waitcnt lgkmcnt(10)
	v_pk_fma_f32 v[114:115], v[40:41], v[64:65], v[114:115] op_sel_hi:[1,0,1]
	ds_read_b128 v[84:87], v6 offset:21760
	v_add_f32_dpp v10, v10, v10 row_ror:2 row_mask:0xf bank_mask:0xf bound_ctrl:1
	v_add_f32_dpp v12, v12, v12 row_ror:2 row_mask:0xf bank_mask:0xf bound_ctrl:1
	v_pk_fma_f32 v[116:117], v[42:43], v[64:65], v[116:117] op_sel_hi:[1,0,1]
	ds_read_b128 v[88:91], v6 offset:22016
	v_add_f32_dpp v10, v10, v10 row_ror:1 row_mask:0xf bank_mask:0xf bound_ctrl:1
	v_add_f32_dpp v12, v12, v12 row_ror:1 row_mask:0xf bank_mask:0xf bound_ctrl:1
	v_fmac_f32_e32 v14, v64, v59
	ds_read2_b32 v[112:113], v120 offset0:32 offset1:48
	s_waitcnt lgkmcnt(9)
	v_pk_fma_f32 v[114:115], v[48:49], v[64:65], v[114:115] op_sel:[0,1,0] op_sel_hi:[1,1,1]
	v_fmac_f32_e32 v12, v64, v57
	v_pk_fma_f32 v[116:117], v[50:51], v[64:65], v[116:117] op_sel:[0,1,0] op_sel_hi:[1,1,1]
	ds_read_b128 v[96:99], v6 offset:22528
	v_fmac_f32_e32 v15, v64, v61
	v_pk_fma_f32 v[114:115], v[44:45], v[10:11], v[114:115] op_sel_hi:[1,0,1] neg_lo:[1,0,0] neg_hi:[1,0,0]
	v_fmac_f32_e32 v15, v65, v63
	ds_read_b128 v[92:95], v6 offset:22272
	v_pk_fma_f32 v[116:117], v[46:47], v[10:11], v[116:117] op_sel_hi:[1,0,1] neg_lo:[1,0,0] neg_hi:[1,0,0]
	v_fma_f32 v14, -v10, v58, v14
	v_fma_f32 v15, -v10, v60, v15
	ds_read_b128 v[100:103], v6 offset:22784
	v_fma_f32 v15, -v12, v62, v15
	v_pk_fma_f32 v[2:3], v[52:53], v[12:13], v[114:115] op_sel_hi:[1,0,1] neg_lo:[1,0,0] neg_hi:[1,0,0]
	v_pk_fma_f32 v[4:5], v[54:55], v[12:13], v[116:117] op_sel_hi:[1,0,1] neg_lo:[1,0,0] neg_hi:[1,0,0]
	ds_read_b128 v[108:111], v7 offset:37312
	ds_write2st64_b32 v9, v14, v15 offset0:64 offset1:68
	s_waitcnt lgkmcnt(8)
	v_pk_mul_f32 v[10:11], v[2:3], v[68:69] op_sel_hi:[0,1]
	ds_read_b128 v[20:23], v6 offset:23040
	v_pk_mul_f32 v[14:15], v[2:3], v[72:73] op_sel_hi:[0,1]
	v_pk_fma_f32 v[10:11], v[2:3], v[70:71], v[10:11] op_sel:[1,0,0] op_sel_hi:[1,1,1]
	v_pk_fma_f32 v[14:15], v[2:3], v[74:75], v[14:15] op_sel:[1,0,0] op_sel_hi:[1,1,1]
	ds_read_b128 v[28:31], v6 offset:23552
	v_pk_fma_f32 v[10:11], v[4:5], v[76:77], v[10:11] op_sel_hi:[0,1,1]
	v_pk_fma_f32 v[14:15], v[4:5], v[80:81], v[14:15] op_sel_hi:[0,1,1]
	v_pk_fma_f32 v[10:11], v[4:5], v[78:79], v[10:11] op_sel:[1,0,0] op_sel_hi:[1,1,1]
	ds_read_b128 v[24:27], v6 offset:23296
	v_pk_fma_f32 v[14:15], v[4:5], v[82:83], v[14:15] op_sel:[1,0,0] op_sel_hi:[1,1,1]
	v_fma_f32 v12, -v104, v10, v11
	s_waitcnt lgkmcnt(10)
	v_pk_mul_f32 v[114:115], v[2:3], v[84:85]
	ds_read_b128 v[32:35], v6 offset:23808
	v_add_f32_dpp v10, v10, v10 row_ror:8 row_mask:0xf bank_mask:0xf bound_ctrl:1
	v_add_f32_dpp v12, v12, v12 row_ror:8 row_mask:0xf bank_mask:0xf bound_ctrl:1
	v_pk_mul_f32 v[116:117], v[4:5], v[86:87]
	ds_read_b128 v[56:59], v7 offset:37344
	v_add_f32_dpp v10, v10, v10 row_ror:4 row_mask:0xf bank_mask:0xf bound_ctrl:1
	v_add_f32_dpp v12, v12, v12 row_ror:4 row_mask:0xf bank_mask:0xf bound_ctrl:1
	s_waitcnt lgkmcnt(10)
	v_pk_fma_f32 v[114:115], v[88:89], v[112:113], v[114:115] op_sel_hi:[1,0,1]
	ds_read_b128 v[36:39], v6 offset:24064
	v_add_f32_dpp v10, v10, v10 row_ror:2 row_mask:0xf bank_mask:0xf bound_ctrl:1
	v_add_f32_dpp v12, v12, v12 row_ror:2 row_mask:0xf bank_mask:0xf bound_ctrl:1
	v_pk_fma_f32 v[116:117], v[90:91], v[112:113], v[116:117] op_sel_hi:[1,0,1]
	ds_read_b128 v[40:43], v6 offset:24320
	v_add_f32_dpp v10, v10, v10 row_ror:1 row_mask:0xf bank_mask:0xf bound_ctrl:1
	v_add_f32_dpp v12, v12, v12 row_ror:1 row_mask:0xf bank_mask:0xf bound_ctrl:1
	v_fmac_f32_e32 v14, v112, v107
	ds_read2_b32 v[64:65], v120 offset0:64 offset1:80
	s_waitcnt lgkmcnt(9)
	v_pk_fma_f32 v[114:115], v[96:97], v[112:113], v[114:115] op_sel:[0,1,0] op_sel_hi:[1,1,1]
	v_fmac_f32_e32 v12, v112, v105
	v_pk_fma_f32 v[116:117], v[98:99], v[112:113], v[116:117] op_sel:[0,1,0] op_sel_hi:[1,1,1]
	ds_read_b128 v[48:51], v6 offset:24832
	v_fmac_f32_e32 v15, v112, v109
	v_pk_fma_f32 v[114:115], v[92:93], v[10:11], v[114:115] op_sel_hi:[1,0,1] neg_lo:[1,0,0] neg_hi:[1,0,0]
	v_fmac_f32_e32 v15, v113, v111
	ds_read_b128 v[44:47], v6 offset:24576
	v_pk_fma_f32 v[116:117], v[94:95], v[10:11], v[116:117] op_sel_hi:[1,0,1] neg_lo:[1,0,0] neg_hi:[1,0,0]
	v_fma_f32 v14, -v10, v106, v14
	v_fma_f32 v15, -v10, v108, v15
	ds_read_b128 v[52:55], v6 offset:25088
	v_fma_f32 v15, -v12, v110, v15
	v_pk_fma_f32 v[2:3], v[100:101], v[12:13], v[114:115] op_sel_hi:[1,0,1] neg_lo:[1,0,0] neg_hi:[1,0,0]
	v_pk_fma_f32 v[4:5], v[102:103], v[12:13], v[116:117] op_sel_hi:[1,0,1] neg_lo:[1,0,0] neg_hi:[1,0,0]
	ds_read_b128 v[60:63], v7 offset:37360
	ds_write2st64_b32 v9, v14, v15 offset0:72 offset1:76
	s_waitcnt lgkmcnt(8)
	v_pk_mul_f32 v[10:11], v[2:3], v[20:21] op_sel_hi:[0,1]
	ds_read_b128 v[68:71], v6 offset:25344
	v_pk_mul_f32 v[14:15], v[2:3], v[24:25] op_sel_hi:[0,1]
	v_pk_fma_f32 v[10:11], v[2:3], v[22:23], v[10:11] op_sel:[1,0,0] op_sel_hi:[1,1,1]
	v_pk_fma_f32 v[14:15], v[2:3], v[26:27], v[14:15] op_sel:[1,0,0] op_sel_hi:[1,1,1]
	ds_read_b128 v[76:79], v6 offset:25856
	v_pk_fma_f32 v[10:11], v[4:5], v[28:29], v[10:11] op_sel_hi:[0,1,1]
	v_pk_fma_f32 v[14:15], v[4:5], v[32:33], v[14:15] op_sel_hi:[0,1,1]
	v_pk_fma_f32 v[10:11], v[4:5], v[30:31], v[10:11] op_sel:[1,0,0] op_sel_hi:[1,1,1]
	ds_read_b128 v[72:75], v6 offset:25600
	v_pk_fma_f32 v[14:15], v[4:5], v[34:35], v[14:15] op_sel:[1,0,0] op_sel_hi:[1,1,1]
	v_fma_f32 v12, -v56, v10, v11
	s_waitcnt lgkmcnt(10)
	v_pk_mul_f32 v[114:115], v[2:3], v[36:37]
	ds_read_b128 v[80:83], v6 offset:26112
	v_add_f32_dpp v10, v10, v10 row_ror:8 row_mask:0xf bank_mask:0xf bound_ctrl:1
	v_add_f32_dpp v12, v12, v12 row_ror:8 row_mask:0xf bank_mask:0xf bound_ctrl:1
	v_pk_mul_f32 v[116:117], v[4:5], v[38:39]
	ds_read_b128 v[104:107], v7 offset:37392
	v_add_f32_dpp v10, v10, v10 row_ror:4 row_mask:0xf bank_mask:0xf bound_ctrl:1
	v_add_f32_dpp v12, v12, v12 row_ror:4 row_mask:0xf bank_mask:0xf bound_ctrl:1
	s_waitcnt lgkmcnt(10)
	v_pk_fma_f32 v[114:115], v[40:41], v[64:65], v[114:115] op_sel_hi:[1,0,1]
	ds_read_b128 v[84:87], v6 offset:26368
	v_add_f32_dpp v10, v10, v10 row_ror:2 row_mask:0xf bank_mask:0xf bound_ctrl:1
	v_add_f32_dpp v12, v12, v12 row_ror:2 row_mask:0xf bank_mask:0xf bound_ctrl:1
	v_pk_fma_f32 v[116:117], v[42:43], v[64:65], v[116:117] op_sel_hi:[1,0,1]
	ds_read_b128 v[88:91], v6 offset:26624
	v_add_f32_dpp v10, v10, v10 row_ror:1 row_mask:0xf bank_mask:0xf bound_ctrl:1
	v_add_f32_dpp v12, v12, v12 row_ror:1 row_mask:0xf bank_mask:0xf bound_ctrl:1
	v_fmac_f32_e32 v14, v64, v59
	ds_read2_b32 v[112:113], v120 offset0:96 offset1:112
	s_waitcnt lgkmcnt(9)
	v_pk_fma_f32 v[114:115], v[48:49], v[64:65], v[114:115] op_sel:[0,1,0] op_sel_hi:[1,1,1]
	v_fmac_f32_e32 v12, v64, v57
	v_pk_fma_f32 v[116:117], v[50:51], v[64:65], v[116:117] op_sel:[0,1,0] op_sel_hi:[1,1,1]
	ds_read_b128 v[96:99], v6 offset:27136
	v_fmac_f32_e32 v15, v64, v61
	v_pk_fma_f32 v[114:115], v[44:45], v[10:11], v[114:115] op_sel_hi:[1,0,1] neg_lo:[1,0,0] neg_hi:[1,0,0]
	v_fmac_f32_e32 v15, v65, v63
	ds_read_b128 v[92:95], v6 offset:26880
	v_pk_fma_f32 v[116:117], v[46:47], v[10:11], v[116:117] op_sel_hi:[1,0,1] neg_lo:[1,0,0] neg_hi:[1,0,0]
	v_fma_f32 v14, -v10, v58, v14
	v_fma_f32 v15, -v10, v60, v15
	ds_read_b128 v[100:103], v6 offset:27392
	v_fma_f32 v15, -v12, v62, v15
	v_pk_fma_f32 v[2:3], v[52:53], v[12:13], v[114:115] op_sel_hi:[1,0,1] neg_lo:[1,0,0] neg_hi:[1,0,0]
	v_pk_fma_f32 v[4:5], v[54:55], v[12:13], v[116:117] op_sel_hi:[1,0,1] neg_lo:[1,0,0] neg_hi:[1,0,0]
	ds_read_b128 v[108:111], v7 offset:37408
	ds_write2st64_b32 v9, v14, v15 offset0:80 offset1:84
	s_waitcnt lgkmcnt(8)
	v_pk_mul_f32 v[10:11], v[2:3], v[68:69] op_sel_hi:[0,1]
	ds_read_b128 v[20:23], v6 offset:27648
	v_pk_mul_f32 v[14:15], v[2:3], v[72:73] op_sel_hi:[0,1]
	v_pk_fma_f32 v[10:11], v[2:3], v[70:71], v[10:11] op_sel:[1,0,0] op_sel_hi:[1,1,1]
	v_pk_fma_f32 v[14:15], v[2:3], v[74:75], v[14:15] op_sel:[1,0,0] op_sel_hi:[1,1,1]
	ds_read_b128 v[28:31], v6 offset:28160
	v_pk_fma_f32 v[10:11], v[4:5], v[76:77], v[10:11] op_sel_hi:[0,1,1]
	v_pk_fma_f32 v[14:15], v[4:5], v[80:81], v[14:15] op_sel_hi:[0,1,1]
	v_pk_fma_f32 v[10:11], v[4:5], v[78:79], v[10:11] op_sel:[1,0,0] op_sel_hi:[1,1,1]
	ds_read_b128 v[24:27], v6 offset:27904
	v_pk_fma_f32 v[14:15], v[4:5], v[82:83], v[14:15] op_sel:[1,0,0] op_sel_hi:[1,1,1]
	v_fma_f32 v12, -v104, v10, v11
	s_waitcnt lgkmcnt(10)
	v_pk_mul_f32 v[114:115], v[2:3], v[84:85]
	ds_read_b128 v[32:35], v6 offset:28416
	v_add_f32_dpp v10, v10, v10 row_ror:8 row_mask:0xf bank_mask:0xf bound_ctrl:1
	v_add_f32_dpp v12, v12, v12 row_ror:8 row_mask:0xf bank_mask:0xf bound_ctrl:1
	v_pk_mul_f32 v[116:117], v[4:5], v[86:87]
	ds_read_b128 v[56:59], v7 offset:37440
	v_add_f32_dpp v10, v10, v10 row_ror:4 row_mask:0xf bank_mask:0xf bound_ctrl:1
	v_add_f32_dpp v12, v12, v12 row_ror:4 row_mask:0xf bank_mask:0xf bound_ctrl:1
	s_waitcnt lgkmcnt(10)
	v_pk_fma_f32 v[114:115], v[88:89], v[112:113], v[114:115] op_sel_hi:[1,0,1]
	ds_read_b128 v[36:39], v6 offset:28672
	v_add_f32_dpp v10, v10, v10 row_ror:2 row_mask:0xf bank_mask:0xf bound_ctrl:1
	v_add_f32_dpp v12, v12, v12 row_ror:2 row_mask:0xf bank_mask:0xf bound_ctrl:1
	v_pk_fma_f32 v[116:117], v[90:91], v[112:113], v[116:117] op_sel_hi:[1,0,1]
	ds_read_b128 v[40:43], v6 offset:28928
	v_add_f32_dpp v10, v10, v10 row_ror:1 row_mask:0xf bank_mask:0xf bound_ctrl:1
	v_add_f32_dpp v12, v12, v12 row_ror:1 row_mask:0xf bank_mask:0xf bound_ctrl:1
	v_fmac_f32_e32 v14, v112, v107
	ds_read2_b32 v[64:65], v120 offset0:128 offset1:144
	s_waitcnt lgkmcnt(9)
	v_pk_fma_f32 v[114:115], v[96:97], v[112:113], v[114:115] op_sel:[0,1,0] op_sel_hi:[1,1,1]
	v_fmac_f32_e32 v12, v112, v105
	v_pk_fma_f32 v[116:117], v[98:99], v[112:113], v[116:117] op_sel:[0,1,0] op_sel_hi:[1,1,1]
	ds_read_b128 v[48:51], v6 offset:29440
	v_fmac_f32_e32 v15, v112, v109
	v_pk_fma_f32 v[114:115], v[92:93], v[10:11], v[114:115] op_sel_hi:[1,0,1] neg_lo:[1,0,0] neg_hi:[1,0,0]
	v_fmac_f32_e32 v15, v113, v111
	ds_read_b128 v[44:47], v6 offset:29184
	v_pk_fma_f32 v[116:117], v[94:95], v[10:11], v[116:117] op_sel_hi:[1,0,1] neg_lo:[1,0,0] neg_hi:[1,0,0]
	v_fma_f32 v14, -v10, v106, v14
	v_fma_f32 v15, -v10, v108, v15
	ds_read_b128 v[52:55], v6 offset:29696
	v_fma_f32 v15, -v12, v110, v15
	v_pk_fma_f32 v[2:3], v[100:101], v[12:13], v[114:115] op_sel_hi:[1,0,1] neg_lo:[1,0,0] neg_hi:[1,0,0]
	v_pk_fma_f32 v[4:5], v[102:103], v[12:13], v[116:117] op_sel_hi:[1,0,1] neg_lo:[1,0,0] neg_hi:[1,0,0]
	ds_read_b128 v[60:63], v7 offset:37456
	ds_write2st64_b32 v9, v14, v15 offset0:88 offset1:92
	s_waitcnt lgkmcnt(8)
	v_pk_mul_f32 v[10:11], v[2:3], v[20:21] op_sel_hi:[0,1]
	ds_read_b128 v[68:71], v6 offset:29952
	v_pk_mul_f32 v[14:15], v[2:3], v[24:25] op_sel_hi:[0,1]
	v_pk_fma_f32 v[10:11], v[2:3], v[22:23], v[10:11] op_sel:[1,0,0] op_sel_hi:[1,1,1]
	v_pk_fma_f32 v[14:15], v[2:3], v[26:27], v[14:15] op_sel:[1,0,0] op_sel_hi:[1,1,1]
	ds_read_b128 v[76:79], v6 offset:30464
	v_pk_fma_f32 v[10:11], v[4:5], v[28:29], v[10:11] op_sel_hi:[0,1,1]
	v_pk_fma_f32 v[14:15], v[4:5], v[32:33], v[14:15] op_sel_hi:[0,1,1]
	v_pk_fma_f32 v[10:11], v[4:5], v[30:31], v[10:11] op_sel:[1,0,0] op_sel_hi:[1,1,1]
	ds_read_b128 v[72:75], v6 offset:30208
	v_pk_fma_f32 v[14:15], v[4:5], v[34:35], v[14:15] op_sel:[1,0,0] op_sel_hi:[1,1,1]
	v_fma_f32 v12, -v56, v10, v11
	s_waitcnt lgkmcnt(10)
	v_pk_mul_f32 v[114:115], v[2:3], v[36:37]
	ds_read_b128 v[80:83], v6 offset:30720
	v_add_f32_dpp v10, v10, v10 row_ror:8 row_mask:0xf bank_mask:0xf bound_ctrl:1
	v_add_f32_dpp v12, v12, v12 row_ror:8 row_mask:0xf bank_mask:0xf bound_ctrl:1
	v_pk_mul_f32 v[116:117], v[4:5], v[38:39]
	ds_read_b128 v[104:107], v7 offset:37488
	v_add_f32_dpp v10, v10, v10 row_ror:4 row_mask:0xf bank_mask:0xf bound_ctrl:1
	v_add_f32_dpp v12, v12, v12 row_ror:4 row_mask:0xf bank_mask:0xf bound_ctrl:1
	s_waitcnt lgkmcnt(10)
	v_pk_fma_f32 v[114:115], v[40:41], v[64:65], v[114:115] op_sel_hi:[1,0,1]
	ds_read_b128 v[84:87], v6 offset:30976
	v_add_f32_dpp v10, v10, v10 row_ror:2 row_mask:0xf bank_mask:0xf bound_ctrl:1
	v_add_f32_dpp v12, v12, v12 row_ror:2 row_mask:0xf bank_mask:0xf bound_ctrl:1
	v_pk_fma_f32 v[116:117], v[42:43], v[64:65], v[116:117] op_sel_hi:[1,0,1]
	ds_read_b128 v[88:91], v6 offset:31232
	v_add_f32_dpp v10, v10, v10 row_ror:1 row_mask:0xf bank_mask:0xf bound_ctrl:1
	v_add_f32_dpp v12, v12, v12 row_ror:1 row_mask:0xf bank_mask:0xf bound_ctrl:1
	v_fmac_f32_e32 v14, v64, v59
	ds_read2_b32 v[112:113], v120 offset0:160 offset1:176
	s_waitcnt lgkmcnt(9)
	v_pk_fma_f32 v[114:115], v[48:49], v[64:65], v[114:115] op_sel:[0,1,0] op_sel_hi:[1,1,1]
	v_fmac_f32_e32 v12, v64, v57
	v_pk_fma_f32 v[116:117], v[50:51], v[64:65], v[116:117] op_sel:[0,1,0] op_sel_hi:[1,1,1]
	ds_read_b128 v[96:99], v6 offset:31744
	v_fmac_f32_e32 v15, v64, v61
	v_pk_fma_f32 v[114:115], v[44:45], v[10:11], v[114:115] op_sel_hi:[1,0,1] neg_lo:[1,0,0] neg_hi:[1,0,0]
	v_fmac_f32_e32 v15, v65, v63
	ds_read_b128 v[92:95], v6 offset:31488
	v_pk_fma_f32 v[116:117], v[46:47], v[10:11], v[116:117] op_sel_hi:[1,0,1] neg_lo:[1,0,0] neg_hi:[1,0,0]
	v_fma_f32 v14, -v10, v58, v14
	v_fma_f32 v15, -v10, v60, v15
	ds_read_b128 v[100:103], v6 offset:32000
	v_fma_f32 v15, -v12, v62, v15
	v_pk_fma_f32 v[2:3], v[52:53], v[12:13], v[114:115] op_sel_hi:[1,0,1] neg_lo:[1,0,0] neg_hi:[1,0,0]
	v_pk_fma_f32 v[4:5], v[54:55], v[12:13], v[116:117] op_sel_hi:[1,0,1] neg_lo:[1,0,0] neg_hi:[1,0,0]
	ds_read_b128 v[108:111], v7 offset:37504
	ds_write2st64_b32 v9, v14, v15 offset0:96 offset1:100
	s_waitcnt lgkmcnt(8)
	v_pk_mul_f32 v[10:11], v[2:3], v[68:69] op_sel_hi:[0,1]
	ds_read_b128 v[20:23], v6 offset:32256
	v_pk_mul_f32 v[14:15], v[2:3], v[72:73] op_sel_hi:[0,1]
	v_pk_fma_f32 v[10:11], v[2:3], v[70:71], v[10:11] op_sel:[1,0,0] op_sel_hi:[1,1,1]
	v_pk_fma_f32 v[14:15], v[2:3], v[74:75], v[14:15] op_sel:[1,0,0] op_sel_hi:[1,1,1]
	ds_read_b128 v[28:31], v6 offset:32768
	v_pk_fma_f32 v[10:11], v[4:5], v[76:77], v[10:11] op_sel_hi:[0,1,1]
	v_pk_fma_f32 v[14:15], v[4:5], v[80:81], v[14:15] op_sel_hi:[0,1,1]
	v_pk_fma_f32 v[10:11], v[4:5], v[78:79], v[10:11] op_sel:[1,0,0] op_sel_hi:[1,1,1]
	ds_read_b128 v[24:27], v6 offset:32512
	v_pk_fma_f32 v[14:15], v[4:5], v[82:83], v[14:15] op_sel:[1,0,0] op_sel_hi:[1,1,1]
	v_fma_f32 v12, -v104, v10, v11
	s_waitcnt lgkmcnt(10)
	v_pk_mul_f32 v[114:115], v[2:3], v[84:85]
	ds_read_b128 v[32:35], v6 offset:33024
	v_add_f32_dpp v10, v10, v10 row_ror:8 row_mask:0xf bank_mask:0xf bound_ctrl:1
	v_add_f32_dpp v12, v12, v12 row_ror:8 row_mask:0xf bank_mask:0xf bound_ctrl:1
	v_pk_mul_f32 v[116:117], v[4:5], v[86:87]
	ds_read_b128 v[56:59], v7 offset:37536
	v_add_f32_dpp v10, v10, v10 row_ror:4 row_mask:0xf bank_mask:0xf bound_ctrl:1
	v_add_f32_dpp v12, v12, v12 row_ror:4 row_mask:0xf bank_mask:0xf bound_ctrl:1
	s_waitcnt lgkmcnt(10)
	v_pk_fma_f32 v[114:115], v[88:89], v[112:113], v[114:115] op_sel_hi:[1,0,1]
	ds_read_b128 v[36:39], v6 offset:33280
	v_add_f32_dpp v10, v10, v10 row_ror:2 row_mask:0xf bank_mask:0xf bound_ctrl:1
	v_add_f32_dpp v12, v12, v12 row_ror:2 row_mask:0xf bank_mask:0xf bound_ctrl:1
	v_pk_fma_f32 v[116:117], v[90:91], v[112:113], v[116:117] op_sel_hi:[1,0,1]
	ds_read_b128 v[40:43], v6 offset:33536
	v_add_f32_dpp v10, v10, v10 row_ror:1 row_mask:0xf bank_mask:0xf bound_ctrl:1
	v_add_f32_dpp v12, v12, v12 row_ror:1 row_mask:0xf bank_mask:0xf bound_ctrl:1
	v_fmac_f32_e32 v14, v112, v107
	ds_read2_b32 v[64:65], v120 offset0:192 offset1:208
	s_waitcnt lgkmcnt(9)
	v_pk_fma_f32 v[114:115], v[96:97], v[112:113], v[114:115] op_sel:[0,1,0] op_sel_hi:[1,1,1]
	v_fmac_f32_e32 v12, v112, v105
	v_pk_fma_f32 v[116:117], v[98:99], v[112:113], v[116:117] op_sel:[0,1,0] op_sel_hi:[1,1,1]
	ds_read_b128 v[48:51], v6 offset:34048
	v_fmac_f32_e32 v15, v112, v109
	v_pk_fma_f32 v[114:115], v[92:93], v[10:11], v[114:115] op_sel_hi:[1,0,1] neg_lo:[1,0,0] neg_hi:[1,0,0]
	v_fmac_f32_e32 v15, v113, v111
	ds_read_b128 v[44:47], v6 offset:33792
	v_pk_fma_f32 v[116:117], v[94:95], v[10:11], v[116:117] op_sel_hi:[1,0,1] neg_lo:[1,0,0] neg_hi:[1,0,0]
	v_fma_f32 v14, -v10, v106, v14
	v_fma_f32 v15, -v10, v108, v15
	ds_read_b128 v[52:55], v6 offset:34304
	v_fma_f32 v15, -v12, v110, v15
	v_pk_fma_f32 v[2:3], v[100:101], v[12:13], v[114:115] op_sel_hi:[1,0,1] neg_lo:[1,0,0] neg_hi:[1,0,0]
	v_pk_fma_f32 v[4:5], v[102:103], v[12:13], v[116:117] op_sel_hi:[1,0,1] neg_lo:[1,0,0] neg_hi:[1,0,0]
	ds_read_b128 v[60:63], v7 offset:37552
	ds_write2st64_b32 v9, v14, v15 offset0:104 offset1:108
	s_waitcnt lgkmcnt(8)
	v_pk_mul_f32 v[10:11], v[2:3], v[20:21] op_sel_hi:[0,1]
	ds_read_b128 v[68:71], v6 offset:34560
	v_pk_mul_f32 v[14:15], v[2:3], v[24:25] op_sel_hi:[0,1]
	v_pk_fma_f32 v[10:11], v[2:3], v[22:23], v[10:11] op_sel:[1,0,0] op_sel_hi:[1,1,1]
	v_pk_fma_f32 v[14:15], v[2:3], v[26:27], v[14:15] op_sel:[1,0,0] op_sel_hi:[1,1,1]
	ds_read_b128 v[76:79], v6 offset:35072
	v_pk_fma_f32 v[10:11], v[4:5], v[28:29], v[10:11] op_sel_hi:[0,1,1]
	v_pk_fma_f32 v[14:15], v[4:5], v[32:33], v[14:15] op_sel_hi:[0,1,1]
	v_pk_fma_f32 v[10:11], v[4:5], v[30:31], v[10:11] op_sel:[1,0,0] op_sel_hi:[1,1,1]
	ds_read_b128 v[72:75], v6 offset:34816
	v_pk_fma_f32 v[14:15], v[4:5], v[34:35], v[14:15] op_sel:[1,0,0] op_sel_hi:[1,1,1]
	v_fma_f32 v12, -v56, v10, v11
	s_waitcnt lgkmcnt(10)
	v_pk_mul_f32 v[114:115], v[2:3], v[36:37]
	ds_read_b128 v[80:83], v6 offset:35328
	v_add_f32_dpp v10, v10, v10 row_ror:8 row_mask:0xf bank_mask:0xf bound_ctrl:1
	v_add_f32_dpp v12, v12, v12 row_ror:8 row_mask:0xf bank_mask:0xf bound_ctrl:1
	v_pk_mul_f32 v[116:117], v[4:5], v[38:39]
	ds_read_b128 v[104:107], v7 offset:37584
	v_add_f32_dpp v10, v10, v10 row_ror:4 row_mask:0xf bank_mask:0xf bound_ctrl:1
	v_add_f32_dpp v12, v12, v12 row_ror:4 row_mask:0xf bank_mask:0xf bound_ctrl:1
	s_waitcnt lgkmcnt(10)
	v_pk_fma_f32 v[114:115], v[40:41], v[64:65], v[114:115] op_sel_hi:[1,0,1]
	ds_read_b128 v[84:87], v6 offset:35584
	v_add_f32_dpp v10, v10, v10 row_ror:2 row_mask:0xf bank_mask:0xf bound_ctrl:1
	v_add_f32_dpp v12, v12, v12 row_ror:2 row_mask:0xf bank_mask:0xf bound_ctrl:1
	v_pk_fma_f32 v[116:117], v[42:43], v[64:65], v[116:117] op_sel_hi:[1,0,1]
	ds_read_b128 v[88:91], v6 offset:35840
	v_add_f32_dpp v10, v10, v10 row_ror:1 row_mask:0xf bank_mask:0xf bound_ctrl:1
	v_add_f32_dpp v12, v12, v12 row_ror:1 row_mask:0xf bank_mask:0xf bound_ctrl:1
	v_fmac_f32_e32 v14, v64, v59
	ds_read2_b32 v[112:113], v120 offset0:224 offset1:240
	s_waitcnt lgkmcnt(9)
	v_pk_fma_f32 v[114:115], v[48:49], v[64:65], v[114:115] op_sel:[0,1,0] op_sel_hi:[1,1,1]
	v_fmac_f32_e32 v12, v64, v57
	v_pk_fma_f32 v[116:117], v[50:51], v[64:65], v[116:117] op_sel:[0,1,0] op_sel_hi:[1,1,1]
	ds_read_b128 v[96:99], v6 offset:36352
	v_fmac_f32_e32 v15, v64, v61
	v_pk_fma_f32 v[114:115], v[44:45], v[10:11], v[114:115] op_sel_hi:[1,0,1] neg_lo:[1,0,0] neg_hi:[1,0,0]
	v_fmac_f32_e32 v15, v65, v63
	ds_read_b128 v[92:95], v6 offset:36096
	v_pk_fma_f32 v[116:117], v[46:47], v[10:11], v[116:117] op_sel_hi:[1,0,1] neg_lo:[1,0,0] neg_hi:[1,0,0]
	v_fma_f32 v14, -v10, v58, v14
	v_fma_f32 v15, -v10, v60, v15
	ds_read_b128 v[100:103], v6 offset:36608
	v_fma_f32 v15, -v12, v62, v15
	v_pk_fma_f32 v[2:3], v[52:53], v[12:13], v[114:115] op_sel_hi:[1,0,1] neg_lo:[1,0,0] neg_hi:[1,0,0]
	v_pk_fma_f32 v[4:5], v[54:55], v[12:13], v[116:117] op_sel_hi:[1,0,1] neg_lo:[1,0,0] neg_hi:[1,0,0]
	ds_read_b128 v[108:111], v7 offset:37600
	ds_write2st64_b32 v9, v14, v15 offset0:112 offset1:116
	s_waitcnt lgkmcnt(8)
	v_pk_mul_f32 v[10:11], v[2:3], v[68:69] op_sel_hi:[0,1]
	v_pk_mul_f32 v[14:15], v[2:3], v[72:73] op_sel_hi:[0,1]
	v_pk_fma_f32 v[10:11], v[2:3], v[70:71], v[10:11] op_sel:[1,0,0] op_sel_hi:[1,1,1]
	v_pk_fma_f32 v[14:15], v[2:3], v[74:75], v[14:15] op_sel:[1,0,0] op_sel_hi:[1,1,1]
	v_pk_fma_f32 v[10:11], v[4:5], v[76:77], v[10:11] op_sel_hi:[0,1,1]
	v_pk_fma_f32 v[14:15], v[4:5], v[80:81], v[14:15] op_sel_hi:[0,1,1]
	v_pk_fma_f32 v[10:11], v[4:5], v[78:79], v[10:11] op_sel:[1,0,0] op_sel_hi:[1,1,1]
	v_pk_fma_f32 v[14:15], v[4:5], v[82:83], v[14:15] op_sel:[1,0,0] op_sel_hi:[1,1,1]
	v_fma_f32 v12, -v104, v10, v11
	s_waitcnt lgkmcnt(7)
	v_pk_mul_f32 v[114:115], v[2:3], v[84:85]
	v_add_f32_dpp v10, v10, v10 row_ror:8 row_mask:0xf bank_mask:0xf bound_ctrl:1
	v_add_f32_dpp v12, v12, v12 row_ror:8 row_mask:0xf bank_mask:0xf bound_ctrl:1
	v_pk_mul_f32 v[116:117], v[4:5], v[86:87]
	v_add_f32_dpp v10, v10, v10 row_ror:4 row_mask:0xf bank_mask:0xf bound_ctrl:1
	v_add_f32_dpp v12, v12, v12 row_ror:4 row_mask:0xf bank_mask:0xf bound_ctrl:1
	s_waitcnt lgkmcnt(5)
	v_pk_fma_f32 v[114:115], v[88:89], v[112:113], v[114:115] op_sel_hi:[1,0,1]
	v_add_f32_dpp v10, v10, v10 row_ror:2 row_mask:0xf bank_mask:0xf bound_ctrl:1
	v_add_f32_dpp v12, v12, v12 row_ror:2 row_mask:0xf bank_mask:0xf bound_ctrl:1
	v_pk_fma_f32 v[116:117], v[90:91], v[112:113], v[116:117] op_sel_hi:[1,0,1]
	v_add_f32_dpp v10, v10, v10 row_ror:1 row_mask:0xf bank_mask:0xf bound_ctrl:1
	v_add_f32_dpp v12, v12, v12 row_ror:1 row_mask:0xf bank_mask:0xf bound_ctrl:1
	v_fmac_f32_e32 v14, v112, v107
	s_waitcnt lgkmcnt(1)
	v_pk_fma_f32 v[114:115], v[96:97], v[112:113], v[114:115] op_sel:[0,1,0] op_sel_hi:[1,1,1]
	v_fmac_f32_e32 v12, v112, v105
	v_pk_fma_f32 v[116:117], v[98:99], v[112:113], v[116:117] op_sel:[0,1,0] op_sel_hi:[1,1,1]
	v_fmac_f32_e32 v15, v112, v109
	v_pk_fma_f32 v[114:115], v[92:93], v[10:11], v[114:115] op_sel_hi:[1,0,1] neg_lo:[1,0,0] neg_hi:[1,0,0]
	v_fmac_f32_e32 v15, v113, v111
	v_pk_fma_f32 v[116:117], v[94:95], v[10:11], v[116:117] op_sel_hi:[1,0,1] neg_lo:[1,0,0] neg_hi:[1,0,0]
	v_fma_f32 v14, -v10, v106, v14
	v_fma_f32 v15, -v10, v108, v15
	v_fma_f32 v15, -v12, v110, v15
	v_pk_fma_f32 v[2:3], v[100:101], v[12:13], v[114:115] op_sel_hi:[1,0,1] neg_lo:[1,0,0] neg_hi:[1,0,0]
	v_pk_fma_f32 v[4:5], v[102:103], v[12:13], v[116:117] op_sel_hi:[1,0,1] neg_lo:[1,0,0] neg_hi:[1,0,0]
	ds_write2st64_b32 v9, v14, v15 offset0:120 offset1:124
	v_add_u32_e32 v6, s1, v6
	v_add_u32_e32 v7, s1, v7
	v_add_u32_e32 v8, s1, v8
	v_add_u32_e32 v9, s1, v9
	v_add_u32_e32 v120, s1, v120
	s_sub_i32 s1, 0, s1
	s_add_i32 s0, s0, 1
	s_cmpk_eq_i32 s0, 0x200
	s_waitcnt lgkmcnt(0)
	s_barrier
	s_cbranch_scc0 .LBB0_652
	s_mov_b64 s[0:1], 0
.LBB0_654:
	s_and_b64 vcc, exec, s[0:1]
	s_cbranch_vccz .LBB0_676
	s_lshl_b32 s0, s2, 8
	s_and_b32 s4, s0, 0x4000
	s_add_u32 s12, s70, 0x4000000
	s_addc_u32 s13, s71, 0
	s_add_u32 s14, s70, 0x8000000
	s_addc_u32 s15, s71, 0
	s_add_u32 s20, s70, 0xc000000
	s_addc_u32 s21, s71, 0
	s_add_u32 s16, s78, 0x30000000
	s_addc_u32 s17, s79, 0
	s_add_u32 s18, s78, 0x34000000
	s_addc_u32 s19, s79, 0
	s_and_b32 s0, s2, 0x60
	s_lshl_b32 s24, s2, 2
	s_bfe_u32 s6, s2, 0x20003
	v_add_u32_e32 v20, 0xffffff00, v153
	s_and_b32 s1, s24, 28
	s_or_b32 s0, s6, s0
	v_ashrrev_i32_e32 v1, 4, v20
	s_or_b32 s25, s0, s1
	v_lshlrev_b32_e32 v26, 1, v1
	s_mov_b32 s5, 0
	s_lshl_b32 s0, s25, 4
	v_and_b32_e32 v23, 15, v153
	v_ashrrev_i32_e32 v27, 31, v26
	s_and_b32 s1, s0, 0x3c0
	v_lshlrev_b32_e32 v22, 2, v23
	v_lshl_add_u64 v[2:3], v[26:27], 0, s[4:5]
	v_or_b32_e32 v55, s1, v22
	v_lshlrev_b64 v[28:29], 10, v[2:3]
	v_or_b32_e32 v2, v28, v55
	v_mov_b32_e32 v3, v29
	v_lshlrev_b64 v[6:7], 1, v[2:3]
	v_lshl_add_u64 v[4:5], s[16:17], 0, v[6:7]
	v_lshl_add_u64 v[2:3], s[70:71], 0, v[6:7]
	global_load_dwordx2 v[8:9], v[4:5], off
	v_lshl_add_u64 v[4:5], s[12:13], 0, v[6:7]
	global_load_dwordx2 v[10:11], v[4:5], off
	v_lshl_add_u64 v[4:5], s[14:15], 0, v[6:7]
	global_load_dwordx2 v[12:13], v[2:3], off
	global_load_dwordx2 v[24:25], v[4:5], off
	global_load_dwordx2 v[14:15], v[2:3], off offset:2048
	v_lshl_add_u64 v[2:3], s[18:19], 0, v[6:7]
	v_or_b32_e32 v6, 0x800, v6
	v_lshl_add_u64 v[4:5], s[12:13], 0, v[6:7]
	global_load_dwordx2 v[16:17], v[4:5], off
	v_lshl_add_u64 v[4:5], s[16:17], 0, v[6:7]
	global_load_dwordx2 v[18:19], v[4:5], off
	global_load_dwordx2 v[38:39], v[2:3], off
	v_ashrrev_i32_e32 v4, 3, v20
	v_ashrrev_i32_e32 v5, 31, v4
	v_lshl_add_u64 v[30:31], s[4:5], 0, v[4:5]
	v_lshlrev_b64 v[32:33], 11, v[30:31]
	v_lshlrev_b32_e32 v2, 1, v153
	s_mov_b32 s7, s5
	v_lshl_add_u64 v[20:21], s[20:21], 0, v[32:33]
	s_and_b32 s0, s0, 48
	s_lshl_b32 s6, s1, 1
	s_mov_b32 s9, s5
	v_and_b32_e32 v58, 14, v2
	s_lshl_b32 s8, s0, 1
	v_lshl_add_u64 v[20:21], v[20:21], 0, s[6:7]
	v_mov_b32_e32 v3, 0
	v_lshlrev_b32_e32 v2, 1, v58
	v_lshl_add_u64 v[20:21], v[20:21], 0, s[8:9]
	v_lshl_add_u64 v[20:21], v[20:21], 0, v[2:3]
	v_lshl_add_u64 v[34:35], s[14:15], 0, v[6:7]
	v_lshl_add_u64 v[6:7], s[18:19], 0, v[6:7]
	global_load_dword v3, v[20:21], off
	global_load_dwordx2 v[40:41], v[34:35], off
	global_load_dwordx2 v[42:43], v[6:7], off
	v_lshl_add_u32 v59, v23, 4, 0
	s_movk_i32 s0, 0x900
	v_mad_i32_i24 v54, v1, s0, v59
	v_cmp_eq_u32_e64 s[0:1], 0, v23
	v_cmp_ne_u32_e32 vcc, 0, v23
	v_mul_i32_i24_e32 v23, 48, v1
	s_waitcnt vmcnt(0)
	v_cvt_f32_f16_e32 v6, v8
	v_cvt_f32_f16_sdwa v7, v8 dst_sel:DWORD dst_unused:UNUSED_PAD src0_sel:WORD_1
	v_cvt_f32_f16_e32 v20, v10
	v_cvt_f32_f16_sdwa v21, v10 dst_sel:DWORD dst_unused:UNUSED_PAD src0_sel:WORD_1
	v_cvt_f32_f16_e32 v44, v12
	v_cvt_f32_f16_sdwa v45, v12 dst_sel:DWORD dst_unused:UNUSED_PAD src0_sel:WORD_1
	v_cvt_f32_f16_e32 v46, v14
	v_cvt_f32_f16_sdwa v47, v14 dst_sel:DWORD dst_unused:UNUSED_PAD src0_sel:WORD_1
	v_cvt_f32_f16_e32 v10, v11
	v_cvt_f32_f16_sdwa v11, v11 dst_sel:DWORD dst_unused:UNUSED_PAD src0_sel:WORD_1
	v_cvt_f32_f16_e32 v48, v13
	v_cvt_f32_f16_sdwa v49, v13 dst_sel:DWORD dst_unused:UNUSED_PAD src0_sel:WORD_1
	v_cvt_f32_f16_e32 v50, v15
	v_cvt_f32_f16_sdwa v51, v15 dst_sel:DWORD dst_unused:UNUSED_PAD src0_sel:WORD_1
	v_cvt_f32_f16_e32 v12, v16
	v_cvt_f32_f16_sdwa v13, v16 dst_sel:DWORD dst_unused:UNUSED_PAD src0_sel:WORD_1
	v_cvt_f32_f16_e32 v14, v17
	v_cvt_f32_f16_sdwa v15, v17 dst_sel:DWORD dst_unused:UNUSED_PAD src0_sel:WORD_1
	v_cvt_f32_f16_e32 v52, v18
	v_cvt_f32_f16_sdwa v53, v18 dst_sel:DWORD dst_unused:UNUSED_PAD src0_sel:WORD_1
	v_cvt_f32_f16_e32 v56, v19
	v_cvt_f32_f16_sdwa v57, v19 dst_sel:DWORD dst_unused:UNUSED_PAD src0_sel:WORD_1
	v_cvt_f32_f16_e32 v8, v9
	v_cvt_f32_f16_sdwa v9, v9 dst_sel:DWORD dst_unused:UNUSED_PAD src0_sel:WORD_1
	v_pk_add_f32 v[20:21], v[20:21], 1.0 op_sel_hi:[1,0] neg_lo:[1,0] neg_hi:[1,0]
	v_pk_add_f32 v[60:61], v[10:11], 1.0 op_sel_hi:[1,0] neg_lo:[1,0] neg_hi:[1,0]
	v_pk_add_f32 v[62:63], v[12:13], 1.0 op_sel_hi:[1,0] neg_lo:[1,0] neg_hi:[1,0]
	v_pk_add_f32 v[64:65], v[14:15], 1.0 op_sel_hi:[1,0] neg_lo:[1,0] neg_hi:[1,0]
	v_pk_mul_f32 v[14:15], v[20:21], v[52:53]
	v_pk_mul_f32 v[16:17], v[60:61], v[56:57]
	v_pk_mul_f32 v[66:67], v[62:63], v[46:47]
	v_pk_mul_f32 v[68:69], v[64:65], v[50:51]
	v_pk_mul_f32 v[10:11], v[20:21], v[44:45]
	v_pk_mul_f32 v[12:13], v[60:61], v[48:49]
	v_pk_mul_f32 v[18:19], v[20:21], v[62:63]
	v_pk_mul_f32 v[34:35], v[20:21], v[66:67]
	v_pk_mul_f32 v[36:37], v[60:61], v[68:69]
	v_pk_mul_f32 v[20:21], v[60:61], v[64:65]
	v_mov_b32_e32 v120, v6
	v_mov_b32_e32 v121, v14
	v_mov_b32_e32 v122, v7
	v_mov_b32_e32 v123, v15
	v_mov_b32_e32 v124, v10
	v_mov_b32_e32 v125, v34
	v_mov_b32_e32 v126, v11
	v_mov_b32_e32 v127, v35
	v_mov_b32_e32 v128, v8
	v_mov_b32_e32 v129, v16
	v_mov_b32_e32 v130, v9
	v_mov_b32_e32 v131, v17
	v_mov_b32_e32 v132, v12
	v_mov_b32_e32 v133, v36
	v_mov_b32_e32 v134, v13
	v_mov_b32_e32 v135, v37
	ds_write_b128 v54, v[120:123]
	ds_write_b128 v54, v[124:127] offset:256
	ds_write_b128 v54, v[128:131] offset:512
	ds_write_b128 v54, v[132:135] offset:768
	ds_write_b128 v54, v[18:21] offset:1024
	v_cvt_f32_f16_e32 v14, v38
	v_cvt_f32_f16_sdwa v16, v38 dst_sel:DWORD dst_unused:UNUSED_PAD src0_sel:WORD_1
	v_cvt_f32_f16_e32 v15, v24
	v_cvt_f32_f16_sdwa v17, v24 dst_sel:DWORD dst_unused:UNUSED_PAD src0_sel:WORD_1
	v_cvt_f32_f16_e32 v21, v25
	v_cvt_f32_f16_sdwa v25, v25 dst_sel:DWORD dst_unused:UNUSED_PAD src0_sel:WORD_1
	v_cvt_f32_f16_e32 v20, v39
	v_cvt_f32_f16_sdwa v24, v39 dst_sel:DWORD dst_unused:UNUSED_PAD src0_sel:WORD_1
	v_mov_b32_e32 v8, v14
	v_mov_b32_e32 v9, v16
	v_mov_b32_e32 v6, v15
	v_mov_b32_e32 v7, v17
	v_pk_mul_f32 v[10:11], v[62:63], v[8:9]
	v_mov_b32_e32 v8, v21
	v_mov_b32_e32 v9, v25
	v_pk_mul_f32 v[6:7], v[62:63], v[6:7]
	v_pk_mul_f32 v[8:9], v[64:65], v[8:9]
	v_mov_b32_e32 v12, v20
	v_mov_b32_e32 v13, v24
	v_mov_b32_e32 v18, v53
	v_pk_mul_f32 v[12:13], v[64:65], v[12:13]
	ds_write_b128 v54, v[6:9] offset:1280
	ds_write_b128 v54, v[10:13] offset:1536
	v_pk_fma_f32 v[6:7], v[52:53], v[14:15], 0 op_sel_hi:[0,1,0]
	v_pk_fma_f32 v[6:7], v[18:19], v[16:17], v[6:7] op_sel_hi:[0,1,1]
	v_mov_b32_e32 v10, v45
	v_pk_fma_f32 v[18:19], v[44:45], v[14:15], 0 op_sel_hi:[0,1,0]
	v_pk_fma_f32 v[14:15], v[66:67], v[14:15], 0 op_sel_hi:[0,1,0]
	v_pk_fma_f32 v[10:11], v[10:11], v[16:17], v[18:19] op_sel_hi:[0,1,1]
	v_pk_fma_f32 v[14:15], v[66:67], v[16:17], v[14:15] op_sel:[1,0,0]
	v_mov_b32_e32 v34, v57
	v_pk_fma_f32 v[6:7], v[56:57], v[20:21], v[6:7] op_sel_hi:[0,1,1]
	v_mov_b32_e32 v12, v49
	v_pk_fma_f32 v[10:11], v[48:49], v[20:21], v[10:11] op_sel_hi:[0,1,1]
	v_pk_fma_f32 v[14:15], v[68:69], v[20:21], v[14:15] op_sel_hi:[0,1,1]
	v_pk_fma_f32 v[6:7], v[34:35], v[24:25], v[6:7] op_sel_hi:[0,1,1]
	v_pk_fma_f32 v[10:11], v[12:13], v[24:25], v[10:11] op_sel_hi:[0,1,1]
	v_pk_fma_f32 v[14:15], v[68:69], v[24:25], v[14:15] op_sel:[1,0,0]
	v_cvt_f32_f16_e32 v25, v40
	v_cvt_f32_f16_sdwa v35, v40 dst_sel:DWORD dst_unused:UNUSED_PAD src0_sel:WORD_1
	v_cvt_f32_f16_e32 v39, v41
	v_cvt_f32_f16_sdwa v41, v41 dst_sel:DWORD dst_unused:UNUSED_PAD src0_sel:WORD_1
	v_cvt_f32_f16_e32 v24, v42
	v_cvt_f32_f16_sdwa v34, v42 dst_sel:DWORD dst_unused:UNUSED_PAD src0_sel:WORD_1
	v_cvt_f32_f16_e32 v38, v43
	v_cvt_f32_f16_sdwa v40, v43 dst_sel:DWORD dst_unused:UNUSED_PAD src0_sel:WORD_1
	v_mov_b32_e32 v18, v25
	v_mov_b32_e32 v19, v35
	v_mov_b32_e32 v20, v39
	v_mov_b32_e32 v21, v41
	ds_write_b128 v54, v[18:21] offset:1792
	v_mov_b32_e32 v18, v24
	v_mov_b32_e32 v19, v34
	v_mov_b32_e32 v20, v38
	v_mov_b32_e32 v21, v40
	v_mov_b32_e32 v36, v47
	ds_write_b128 v54, v[18:21] offset:2048
	v_pk_fma_f32 v[18:19], v[46:47], v[24:25], 0 op_sel_hi:[0,1,0]
	v_pk_fma_f32 v[18:19], v[36:37], v[34:35], v[18:19] op_sel_hi:[0,1,1]
	v_mov_b32_e32 v42, v51
	v_pk_fma_f32 v[18:19], v[50:51], v[38:39], v[18:19] op_sel_hi:[0,1,1]
	v_pk_fma_f32 v[18:19], v[42:43], v[40:41], v[18:19] op_sel_hi:[0,1,1]
	v_mov_b32_dpp v8, v6 row_ror:8 row_mask:0xf bank_mask:0xf bound_ctrl:1
	v_mov_b32_dpp v9, v7 row_ror:8 row_mask:0xf bank_mask:0xf bound_ctrl:1
	v_mov_b32_dpp v12, v10 row_ror:8 row_mask:0xf bank_mask:0xf bound_ctrl:1
	v_mov_b32_dpp v13, v11 row_ror:8 row_mask:0xf bank_mask:0xf bound_ctrl:1
	v_mov_b32_dpp v16, v14 row_ror:8 row_mask:0xf bank_mask:0xf bound_ctrl:1
	v_mov_b32_dpp v17, v15 row_ror:8 row_mask:0xf bank_mask:0xf bound_ctrl:1
	v_mov_b32_dpp v20, v18 row_ror:8 row_mask:0xf bank_mask:0xf bound_ctrl:1
	v_mov_b32_dpp v21, v19 row_ror:8 row_mask:0xf bank_mask:0xf bound_ctrl:1
	v_pk_add_f32 v[6:7], v[6:7], v[8:9]
	v_pk_add_f32 v[10:11], v[10:11], v[12:13]
	v_pk_add_f32 v[14:15], v[14:15], v[16:17]
	v_pk_add_f32 v[18:19], v[18:19], v[20:21]
	v_mov_b32_dpp v8, v6 row_ror:4 row_mask:0xf bank_mask:0xf bound_ctrl:1
	v_mov_b32_dpp v9, v7 row_ror:4 row_mask:0xf bank_mask:0xf bound_ctrl:1
	v_mov_b32_dpp v12, v10 row_ror:4 row_mask:0xf bank_mask:0xf bound_ctrl:1
	v_mov_b32_dpp v13, v11 row_ror:4 row_mask:0xf bank_mask:0xf bound_ctrl:1
	v_mov_b32_dpp v16, v14 row_ror:4 row_mask:0xf bank_mask:0xf bound_ctrl:1
	v_mov_b32_dpp v17, v15 row_ror:4 row_mask:0xf bank_mask:0xf bound_ctrl:1
	v_mov_b32_dpp v20, v18 row_ror:4 row_mask:0xf bank_mask:0xf bound_ctrl:1
	v_mov_b32_dpp v21, v19 row_ror:4 row_mask:0xf bank_mask:0xf bound_ctrl:1
	v_pk_add_f32 v[6:7], v[6:7], v[8:9]
	v_pk_add_f32 v[10:11], v[10:11], v[12:13]
	v_pk_add_f32 v[14:15], v[14:15], v[16:17]
	v_pk_add_f32 v[18:19], v[18:19], v[20:21]
	v_mov_b32_dpp v8, v6 row_ror:2 row_mask:0xf bank_mask:0xf bound_ctrl:1
	v_mov_b32_dpp v9, v7 row_ror:2 row_mask:0xf bank_mask:0xf bound_ctrl:1
	v_mov_b32_dpp v12, v10 row_ror:2 row_mask:0xf bank_mask:0xf bound_ctrl:1
	v_mov_b32_dpp v13, v11 row_ror:2 row_mask:0xf bank_mask:0xf bound_ctrl:1
	v_mov_b32_dpp v16, v14 row_ror:2 row_mask:0xf bank_mask:0xf bound_ctrl:1
	v_mov_b32_dpp v17, v15 row_ror:2 row_mask:0xf bank_mask:0xf bound_ctrl:1
	v_mov_b32_dpp v20, v18 row_ror:2 row_mask:0xf bank_mask:0xf bound_ctrl:1
	v_mov_b32_dpp v21, v19 row_ror:2 row_mask:0xf bank_mask:0xf bound_ctrl:1
	v_pk_add_f32 v[6:7], v[6:7], v[8:9]
	v_pk_add_f32 v[10:11], v[10:11], v[12:13]
	v_pk_add_f32 v[14:15], v[14:15], v[16:17]
	v_pk_add_f32 v[18:19], v[18:19], v[20:21]
	v_mov_b32_dpp v8, v6 row_ror:1 row_mask:0xf bank_mask:0xf bound_ctrl:1
	v_mov_b32_dpp v9, v7 row_ror:1 row_mask:0xf bank_mask:0xf bound_ctrl:1
	v_mov_b32_dpp v12, v10 row_ror:1 row_mask:0xf bank_mask:0xf bound_ctrl:1
	v_mov_b32_dpp v13, v11 row_ror:1 row_mask:0xf bank_mask:0xf bound_ctrl:1
	v_mov_b32_dpp v16, v14 row_ror:1 row_mask:0xf bank_mask:0xf bound_ctrl:1
	v_mov_b32_dpp v17, v15 row_ror:1 row_mask:0xf bank_mask:0xf bound_ctrl:1
	v_mov_b32_dpp v20, v18 row_ror:1 row_mask:0xf bank_mask:0xf bound_ctrl:1
	v_mov_b32_dpp v21, v19 row_ror:1 row_mask:0xf bank_mask:0xf bound_ctrl:1
	s_and_saveexec_b64 s[10:11], vcc
	s_xor_b64 s[10:11], exec, s[10:11]
	v_mul_i32_i24_e32 v23, 48, v1
	s_or_saveexec_b64 s[10:11], s[10:11]
	v_mul_i32_i24_e32 v62, 0x900, v1
	s_xor_b64 exec, exec, s[10:11]
	s_cbranch_execz .LBB0_659
	v_pk_add_f32 v[6:7], v[6:7], v[8:9]
	v_pk_add_f32 v[8:9], v[10:11], v[12:13]
	s_mov_b32 s22, 0x3d800000
	v_pk_mul_f32 v[8:9], v[8:9], s[22:23] op_sel_hi:[1,0]
	v_mad_i32_i24 v1, v1, 48, 0
	ds_write_b128 v1, v[6:9] offset:36864
	v_pk_add_f32 v[6:7], v[14:15], v[16:17]
	v_pk_add_f32 v[8:9], v[18:19], v[20:21]
	v_pk_mul_f32 v[6:7], v[6:7], s[22:23] op_sel_hi:[1,0]
	v_pk_mul_f32 v[8:9], v[8:9], s[22:23] op_sel_hi:[1,0]
	ds_write_b128 v1, v[6:9] offset:36880
.LBB0_659:
	s_or_b64 exec, exec, s[10:11]
	s_or_b32 s22, s4, 32
	s_mov_b32 s23, s5
	v_lshl_add_u64 v[6:7], s[22:23], 0, v[26:27]
	v_lshlrev_b64 v[6:7], 11, v[6:7]
	v_lshlrev_b32_e32 v25, 1, v55
	v_or_b32_e32 v6, v6, v25
	v_lshl_add_u64 v[8:9], s[70:71], 0, v[6:7]
	v_lshl_add_u64 v[10:11], s[12:13], 0, v[6:7]
	v_lshl_add_u64 v[12:13], s[14:15], 0, v[6:7]
	v_lshl_add_u64 v[14:15], s[16:17], 0, v[6:7]
	v_lshl_add_u64 v[16:17], s[18:19], 0, v[6:7]
	v_or_b32_e32 v6, 0x800, v6
	global_load_dwordx2 v[10:11], v[10:11], off
	v_lshl_add_u64 v[18:19], s[12:13], 0, v[6:7]
	global_load_dwordx2 v[14:15], v[14:15], off
	s_nop 0
	global_load_dwordx2 v[18:19], v[18:19], off
	s_nop 0
	global_load_dwordx2 v[20:21], v[8:9], off
	global_load_dwordx2 v[56:57], v[12:13], off
	s_nop 0
	global_load_dwordx2 v[12:13], v[8:9], off offset:2048
	v_lshl_add_u64 v[8:9], s[16:17], 0, v[6:7]
	global_load_dwordx2 v[64:65], v[8:9], off
	global_load_dwordx2 v[68:69], v[16:17], off
	v_cvt_f32_f16_sdwa v9, v3 dst_sel:DWORD dst_unused:UNUSED_PAD src0_sel:WORD_1
	v_cvt_f32_f16_e32 v8, v3
	s_or_b32 s26, s4, 64
	s_mov_b32 s27, s5
	v_lshl_add_u64 v[34:35], s[22:23], 0, v[4:5]
	v_lshl_add_u64 v[36:37], s[26:27], 0, v[26:27]
	v_lshlrev_b32_e32 v1, 6, v4
	s_mov_b32 s11, 0
	v_lshlrev_b32_e32 v24, 2, v58
	v_lshl_add_u64 v[38:39], s[26:27], 0, v[4:5]
	v_lshlrev_b64 v[34:35], 11, v[34:35]
	v_lshlrev_b64 v[36:37], 11, v[36:37]
	v_add3_u32 v1, 0, v1, v24
	s_mov_b32 s7, s11
	v_lshlrev_b64 v[38:39], 11, v[38:39]
	v_lshl_add_u64 v[34:35], s[20:21], 0, v[34:35]
	v_or_b32_e32 v36, v36, v25
	v_lshl_add_u64 v[38:39], s[20:21], 0, v[38:39]
	ds_write_b64 v1, v[8:9] offset:37632
	v_lshl_add_u64 v[8:9], v[34:35], 0, s[6:7]
	v_lshl_add_u64 v[34:35], s[14:15], 0, v[36:37]
	v_lshl_add_u64 v[40:41], s[16:17], 0, v[36:37]
	v_lshl_add_u64 v[50:51], s[14:15], 0, v[6:7]
	v_lshl_add_u64 v[46:47], s[18:19], 0, v[36:37]
	v_lshl_add_u64 v[48:49], v[38:39], 0, s[6:7]
	v_lshl_add_u64 v[6:7], s[18:19], 0, v[6:7]
	global_load_dwordx2 v[38:39], v[34:35], off
	global_load_dwordx2 v[42:43], v[40:41], off
	s_nop 0
	global_load_dwordx2 v[40:41], v[46:47], off
	global_load_dwordx2 v[70:71], v[50:51], off
	global_load_dwordx2 v[72:73], v[6:7], off
	s_add_i32 s10, 0, 0x11b00
	s_mov_b32 s9, s11
	v_lshl_add_u64 v[16:17], s[70:71], 0, v[36:37]
	v_lshl_add_u64 v[44:45], s[12:13], 0, v[36:37]
	v_or_b32_e32 v36, 0x800, v36
	v_mov_b32_e32 v3, 0
	v_lshl_add_u32 v22, v22, 2, s10
	v_lshl_add_u64 v[8:9], v[8:9], 0, s[8:9]
	v_lshl_add_u64 v[34:35], s[12:13], 0, v[36:37]
	v_lshl_add_u64 v[46:47], s[14:15], 0, v[36:37]
	v_lshl_add_u64 v[66:67], s[16:17], 0, v[36:37]
	v_lshl_add_u64 v[36:37], s[18:19], 0, v[36:37]
	v_lshl_add_u64 v[48:49], v[48:49], 0, s[8:9]
	v_add_u32_e32 v76, v22, v62
	v_lshl_add_u64 v[6:7], v[8:9], 0, v[2:3]
	global_load_dwordx2 v[52:53], v[34:35], off
	s_nop 0
	global_load_dwordx2 v[34:35], v[46:47], off
	s_nop 0
	global_load_dwordx2 v[46:47], v[66:67], off
	s_nop 0
	global_load_dwordx2 v[36:37], v[36:37], off
	v_lshl_add_u64 v[8:9], v[48:49], 0, v[2:3]
	global_load_dwordx2 v[50:51], v[44:45], off
	global_load_dword v22, v[6:7], off
	global_load_dwordx2 v[48:49], v[16:17], off
	s_nop 0
	global_load_dwordx2 v[44:45], v[16:17], off offset:2048
	global_load_dword v61, v[8:9], off
	s_waitcnt lgkmcnt(0)
	s_barrier
	v_lshlrev_b32_e32 v60, 4, v4
	v_add_u32_e32 v77, 0, v23
	s_waitcnt vmcnt(19)
	v_cvt_f32_f16_e32 v16, v18
	v_cvt_f32_f16_sdwa v17, v18 dst_sel:DWORD dst_unused:UNUSED_PAD src0_sel:WORD_1
	v_cvt_f32_f16_e32 v8, v10
	v_cvt_f32_f16_sdwa v9, v10 dst_sel:DWORD dst_unused:UNUSED_PAD src0_sel:WORD_1
	v_cvt_f32_f16_e32 v10, v11
	v_pk_add_f32 v[78:79], v[16:17], 1.0 op_sel_hi:[1,0] neg_lo:[1,0] neg_hi:[1,0]
	v_cvt_f32_f16_e32 v16, v19
	v_cvt_f32_f16_sdwa v17, v19 dst_sel:DWORD dst_unused:UNUSED_PAD src0_sel:WORD_1
	v_cvt_f32_f16_sdwa v11, v11 dst_sel:DWORD dst_unused:UNUSED_PAD src0_sel:WORD_1
	s_waitcnt vmcnt(16)
	v_cvt_f32_f16_e32 v80, v12
	v_cvt_f32_f16_sdwa v81, v12 dst_sel:DWORD dst_unused:UNUSED_PAD src0_sel:WORD_1
	s_waitcnt vmcnt(15)
	v_cvt_f32_f16_e32 v82, v64
	v_cvt_f32_f16_sdwa v83, v64 dst_sel:DWORD dst_unused:UNUSED_PAD src0_sel:WORD_1
	v_cvt_f32_f16_e32 v92, v65
	v_cvt_f32_f16_sdwa v93, v65 dst_sel:DWORD dst_unused:UNUSED_PAD src0_sel:WORD_1
	v_cvt_f32_f16_e32 v94, v13
	v_cvt_f32_f16_sdwa v95, v13 dst_sel:DWORD dst_unused:UNUSED_PAD src0_sel:WORD_1
	v_cvt_f32_f16_e32 v6, v14
	v_cvt_f32_f16_sdwa v7, v14 dst_sel:DWORD dst_unused:UNUSED_PAD src0_sel:WORD_1
	v_cvt_f32_f16_e32 v74, v20
	v_pk_add_f32 v[66:67], v[8:9], 1.0 op_sel_hi:[1,0] neg_lo:[1,0] neg_hi:[1,0]
	v_cvt_f32_f16_sdwa v75, v20 dst_sel:DWORD dst_unused:UNUSED_PAD src0_sel:WORD_1
	v_cvt_f32_f16_e32 v8, v15
	v_cvt_f32_f16_sdwa v9, v15 dst_sel:DWORD dst_unused:UNUSED_PAD src0_sel:WORD_1
	v_cvt_f32_f16_e32 v90, v21
	v_cvt_f32_f16_sdwa v91, v21 dst_sel:DWORD dst_unused:UNUSED_PAD src0_sel:WORD_1
	v_pk_add_f32 v[86:87], v[16:17], 1.0 op_sel_hi:[1,0] neg_lo:[1,0] neg_hi:[1,0]
	v_pk_add_f32 v[88:89], v[10:11], 1.0 op_sel_hi:[1,0] neg_lo:[1,0] neg_hi:[1,0]
	v_pk_mul_f32 v[84:85], v[78:79], v[80:81]
	v_pk_mul_f32 v[14:15], v[66:67], v[82:83]
	v_pk_mul_f32 v[16:17], v[88:89], v[92:93]
	v_pk_mul_f32 v[96:97], v[86:87], v[94:95]
	v_pk_mul_f32 v[10:11], v[66:67], v[74:75]
	v_pk_mul_f32 v[12:13], v[88:89], v[90:91]
	v_pk_mul_f32 v[18:19], v[66:67], v[84:85]
	v_pk_mul_f32 v[20:21], v[88:89], v[96:97]
	v_pk_mul_f32 v[64:65], v[66:67], v[78:79]
	v_pk_mul_f32 v[66:67], v[88:89], v[86:87]
	v_mov_b32_e32 v120, v6
	v_mov_b32_e32 v121, v14
	v_mov_b32_e32 v122, v7
	v_mov_b32_e32 v123, v15
	v_mov_b32_e32 v124, v10
	v_mov_b32_e32 v125, v18
	v_mov_b32_e32 v126, v11
	v_mov_b32_e32 v127, v19
	v_mov_b32_e32 v128, v8
	v_mov_b32_e32 v129, v16
	v_mov_b32_e32 v130, v9
	v_mov_b32_e32 v131, v17
	v_mov_b32_e32 v132, v12
	v_mov_b32_e32 v133, v20
	v_mov_b32_e32 v134, v13
	v_mov_b32_e32 v135, v21
	ds_write_b128 v76, v[120:123]
	ds_write_b128 v76, v[124:127] offset:256
	ds_write_b128 v76, v[128:131] offset:512
	ds_write_b128 v76, v[132:135] offset:768
	ds_write_b128 v76, v[64:67] offset:1024
	s_waitcnt vmcnt(14)
	v_cvt_f32_f16_e32 v14, v68
	v_cvt_f32_f16_sdwa v16, v68 dst_sel:DWORD dst_unused:UNUSED_PAD src0_sel:WORD_1
	v_cvt_f32_f16_e32 v15, v56
	v_cvt_f32_f16_sdwa v17, v56 dst_sel:DWORD dst_unused:UNUSED_PAD src0_sel:WORD_1
	v_cvt_f32_f16_e32 v21, v57
	v_cvt_f32_f16_sdwa v57, v57 dst_sel:DWORD dst_unused:UNUSED_PAD src0_sel:WORD_1
	v_cvt_f32_f16_e32 v20, v69
	v_cvt_f32_f16_sdwa v56, v69 dst_sel:DWORD dst_unused:UNUSED_PAD src0_sel:WORD_1
	v_mov_b32_e32 v8, v14
	v_mov_b32_e32 v9, v16
	v_mov_b32_e32 v6, v15
	v_mov_b32_e32 v7, v17
	v_pk_mul_f32 v[10:11], v[78:79], v[8:9]
	v_mov_b32_e32 v8, v21
	v_mov_b32_e32 v9, v57
	v_pk_mul_f32 v[6:7], v[78:79], v[6:7]
	v_pk_mul_f32 v[8:9], v[86:87], v[8:9]
	v_mov_b32_e32 v12, v20
	v_mov_b32_e32 v13, v56
	v_mov_b32_e32 v18, v83
	v_pk_mul_f32 v[12:13], v[86:87], v[12:13]
	ds_write_b128 v76, v[6:9] offset:1280
	ds_write_b128 v76, v[10:13] offset:1536
	v_pk_fma_f32 v[6:7], v[82:83], v[14:15], 0 op_sel_hi:[0,1,0]
	v_pk_fma_f32 v[6:7], v[18:19], v[16:17], v[6:7] op_sel_hi:[0,1,1]
	v_mov_b32_e32 v10, v75
	v_pk_fma_f32 v[18:19], v[74:75], v[14:15], 0 op_sel_hi:[0,1,0]
	v_pk_fma_f32 v[14:15], v[84:85], v[14:15], 0 op_sel_hi:[0,1,0]
	v_pk_fma_f32 v[10:11], v[10:11], v[16:17], v[18:19] op_sel_hi:[0,1,1]
	v_pk_fma_f32 v[14:15], v[84:85], v[16:17], v[14:15] op_sel:[1,0,0]
	v_mov_b32_e32 v54, v93
	v_pk_fma_f32 v[6:7], v[92:93], v[20:21], v[6:7] op_sel_hi:[0,1,1]
	v_mov_b32_e32 v12, v91
	v_pk_fma_f32 v[10:11], v[90:91], v[20:21], v[10:11] op_sel_hi:[0,1,1]
	v_pk_fma_f32 v[14:15], v[96:97], v[20:21], v[14:15] op_sel_hi:[0,1,1]
	v_pk_fma_f32 v[6:7], v[54:55], v[56:57], v[6:7] op_sel_hi:[0,1,1]
	v_pk_fma_f32 v[10:11], v[12:13], v[56:57], v[10:11] op_sel_hi:[0,1,1]
	v_pk_fma_f32 v[14:15], v[96:97], v[56:57], v[14:15] op_sel:[1,0,0]
	s_waitcnt vmcnt(10)
	v_cvt_f32_f16_e32 v57, v70
	v_cvt_f32_f16_sdwa v65, v70 dst_sel:DWORD dst_unused:UNUSED_PAD src0_sel:WORD_1
	v_cvt_f32_f16_e32 v67, v71
	v_cvt_f32_f16_sdwa v69, v71 dst_sel:DWORD dst_unused:UNUSED_PAD src0_sel:WORD_1
	s_waitcnt vmcnt(9)
	v_cvt_f32_f16_e32 v56, v72
	v_cvt_f32_f16_sdwa v64, v72 dst_sel:DWORD dst_unused:UNUSED_PAD src0_sel:WORD_1
	v_cvt_f32_f16_e32 v66, v73
	v_cvt_f32_f16_sdwa v68, v73 dst_sel:DWORD dst_unused:UNUSED_PAD src0_sel:WORD_1
	v_mov_b32_e32 v18, v57
	v_mov_b32_e32 v19, v65
	v_mov_b32_e32 v20, v67
	v_mov_b32_e32 v21, v69
	ds_write_b128 v76, v[18:21] offset:1792
	v_mov_b32_e32 v18, v56
	v_mov_b32_e32 v19, v64
	v_mov_b32_e32 v20, v66
	v_mov_b32_e32 v21, v68
	v_mov_b32_e32 v54, v81
	ds_write_b128 v76, v[18:21] offset:2048
	v_pk_fma_f32 v[18:19], v[80:81], v[56:57], 0 op_sel_hi:[0,1,0]
	v_pk_fma_f32 v[18:19], v[54:55], v[64:65], v[18:19] op_sel_hi:[0,1,1]
	v_mov_b32_e32 v70, v95
	v_pk_fma_f32 v[18:19], v[94:95], v[66:67], v[18:19] op_sel_hi:[0,1,1]
	v_pk_fma_f32 v[18:19], v[70:71], v[68:69], v[18:19] op_sel_hi:[0,1,1]
	v_mov_b32_dpp v8, v6 row_ror:8 row_mask:0xf bank_mask:0xf bound_ctrl:1
	v_mov_b32_dpp v9, v7 row_ror:8 row_mask:0xf bank_mask:0xf bound_ctrl:1
	v_mov_b32_dpp v12, v10 row_ror:8 row_mask:0xf bank_mask:0xf bound_ctrl:1
	v_mov_b32_dpp v13, v11 row_ror:8 row_mask:0xf bank_mask:0xf bound_ctrl:1
	v_mov_b32_dpp v16, v14 row_ror:8 row_mask:0xf bank_mask:0xf bound_ctrl:1
	v_mov_b32_dpp v17, v15 row_ror:8 row_mask:0xf bank_mask:0xf bound_ctrl:1
	v_mov_b32_dpp v20, v18 row_ror:8 row_mask:0xf bank_mask:0xf bound_ctrl:1
	v_mov_b32_dpp v21, v19 row_ror:8 row_mask:0xf bank_mask:0xf bound_ctrl:1
	v_pk_add_f32 v[6:7], v[6:7], v[8:9]
	v_pk_add_f32 v[10:11], v[10:11], v[12:13]
	v_pk_add_f32 v[14:15], v[14:15], v[16:17]
	v_pk_add_f32 v[18:19], v[18:19], v[20:21]
	v_mov_b32_dpp v8, v6 row_ror:4 row_mask:0xf bank_mask:0xf bound_ctrl:1
	v_mov_b32_dpp v9, v7 row_ror:4 row_mask:0xf bank_mask:0xf bound_ctrl:1
	v_mov_b32_dpp v12, v10 row_ror:4 row_mask:0xf bank_mask:0xf bound_ctrl:1
	v_mov_b32_dpp v13, v11 row_ror:4 row_mask:0xf bank_mask:0xf bound_ctrl:1
	v_mov_b32_dpp v16, v14 row_ror:4 row_mask:0xf bank_mask:0xf bound_ctrl:1
	v_mov_b32_dpp v17, v15 row_ror:4 row_mask:0xf bank_mask:0xf bound_ctrl:1
	v_mov_b32_dpp v20, v18 row_ror:4 row_mask:0xf bank_mask:0xf bound_ctrl:1
	v_mov_b32_dpp v21, v19 row_ror:4 row_mask:0xf bank_mask:0xf bound_ctrl:1
	v_pk_add_f32 v[6:7], v[6:7], v[8:9]
	v_pk_add_f32 v[10:11], v[10:11], v[12:13]
	v_pk_add_f32 v[14:15], v[14:15], v[16:17]
	v_pk_add_f32 v[18:19], v[18:19], v[20:21]
	v_mov_b32_dpp v8, v6 row_ror:2 row_mask:0xf bank_mask:0xf bound_ctrl:1
	v_mov_b32_dpp v9, v7 row_ror:2 row_mask:0xf bank_mask:0xf bound_ctrl:1
	v_mov_b32_dpp v12, v10 row_ror:2 row_mask:0xf bank_mask:0xf bound_ctrl:1
	v_mov_b32_dpp v13, v11 row_ror:2 row_mask:0xf bank_mask:0xf bound_ctrl:1
	v_mov_b32_dpp v16, v14 row_ror:2 row_mask:0xf bank_mask:0xf bound_ctrl:1
	v_mov_b32_dpp v17, v15 row_ror:2 row_mask:0xf bank_mask:0xf bound_ctrl:1
	v_mov_b32_dpp v20, v18 row_ror:2 row_mask:0xf bank_mask:0xf bound_ctrl:1
	v_mov_b32_dpp v21, v19 row_ror:2 row_mask:0xf bank_mask:0xf bound_ctrl:1
	v_pk_add_f32 v[6:7], v[6:7], v[8:9]
	v_pk_add_f32 v[10:11], v[10:11], v[12:13]
	v_pk_add_f32 v[14:15], v[14:15], v[16:17]
	v_pk_add_f32 v[18:19], v[18:19], v[20:21]
	v_mov_b32_dpp v8, v6 row_ror:1 row_mask:0xf bank_mask:0xf bound_ctrl:1
	v_mov_b32_dpp v9, v7 row_ror:1 row_mask:0xf bank_mask:0xf bound_ctrl:1
	v_mov_b32_dpp v12, v10 row_ror:1 row_mask:0xf bank_mask:0xf bound_ctrl:1
	v_mov_b32_dpp v13, v11 row_ror:1 row_mask:0xf bank_mask:0xf bound_ctrl:1
	v_mov_b32_dpp v16, v14 row_ror:1 row_mask:0xf bank_mask:0xf bound_ctrl:1
	v_mov_b32_dpp v17, v15 row_ror:1 row_mask:0xf bank_mask:0xf bound_ctrl:1
	v_mov_b32_dpp v20, v18 row_ror:1 row_mask:0xf bank_mask:0xf bound_ctrl:1
	v_mov_b32_dpp v21, v19 row_ror:1 row_mask:0xf bank_mask:0xf bound_ctrl:1
	s_and_saveexec_b64 s[22:23], s[0:1]
	s_cbranch_execz .LBB0_661
	v_pk_add_f32 v[6:7], v[6:7], v[8:9]
	v_pk_add_f32 v[8:9], v[10:11], v[12:13]
	s_mov_b32 s10, 0x3d800000
	v_pk_mul_f32 v[8:9], v[8:9], s[10:11] op_sel_hi:[1,0]
	v_add_u32_e32 v10, 0x1ab00, v77
	ds_write_b128 v10, v[6:9]
	v_pk_add_f32 v[6:7], v[14:15], v[16:17]
	v_pk_add_f32 v[8:9], v[18:19], v[20:21]
	v_pk_mul_f32 v[6:7], v[6:7], s[10:11] op_sel_hi:[1,0]
	v_pk_mul_f32 v[8:9], v[8:9], s[10:11] op_sel_hi:[1,0]
	ds_write_b128 v10, v[6:9] offset:16
.LBB0_661:
	s_or_b64 exec, exec, s[22:23]
	v_lshlrev_b32_e32 v6, 2, v60
	s_add_i32 s7, 0, 0x1ae00
	v_add3_u32 v78, s7, v6, v24
	s_add_u32 s7, s20, s6
	s_addc_u32 s9, s21, 0
	s_add_u32 s20, s7, s8
	s_waitcnt vmcnt(3)
	v_cvt_f32_f16_sdwa v7, v22 dst_sel:DWORD dst_unused:UNUSED_PAD src0_sel:WORD_1
	v_cvt_f32_f16_e32 v6, v22
	s_addc_u32 s21, s9, 0
	v_lshl_add_u64 v[56:57], s[20:21], 0, v[2:3]
	s_mov_b64 s[20:21], 0x18000
	v_or_b32_e32 v54, 0x400, v55
	v_lshl_add_u64 v[16:17], v[28:29], 0, s[20:21]
	ds_write_b64 v78, v[6:7]
	v_or_b32_e32 v6, v16, v55
	v_mov_b32_e32 v7, v17
	v_or_b32_e32 v16, v16, v54
	v_lshlrev_b64 v[12:13], 1, v[6:7]
	v_lshlrev_b64 v[22:23], 1, v[16:17]
	v_lshl_add_u64 v[56:57], v[56:57], 0, v[32:33]
	s_mov_b32 s7, 0x30000
	v_lshl_add_u64 v[6:7], s[70:71], 0, v[12:13]
	v_lshl_add_u64 v[8:9], s[12:13], 0, v[12:13]
	v_lshl_add_u64 v[10:11], s[14:15], 0, v[12:13]
	v_lshl_add_u64 v[14:15], s[16:17], 0, v[12:13]
	v_lshl_add_u64 v[18:19], s[18:19], 0, v[12:13]
	v_lshl_add_u64 v[16:17], s[70:71], 0, v[22:23]
	v_lshl_add_u64 v[20:21], s[12:13], 0, v[22:23]
	v_lshl_add_u64 v[24:25], s[14:15], 0, v[22:23]
	v_add_co_u32_e32 v32, vcc, s7, v56
	global_load_dwordx2 v[6:7], v[6:7], off
	s_nop 0
	global_load_dwordx2 v[8:9], v[8:9], off
	s_nop 0
	global_load_dwordx2 v[10:11], v[10:11], off
	s_nop 0
	global_load_dwordx2 v[12:13], v[14:15], off
	s_nop 0
	global_load_dwordx2 v[14:15], v[18:19], off
	s_nop 0
	global_load_dwordx2 v[18:19], v[16:17], off
	s_nop 0
	global_load_dwordx2 v[16:17], v[20:21], off
	s_nop 0
	global_load_dwordx2 v[20:21], v[24:25], off
	v_lshl_add_u64 v[24:25], s[16:17], 0, v[22:23]
	v_lshl_add_u64 v[22:23], s[18:19], 0, v[22:23]
	v_addc_co_u32_e32 v33, vcc, 0, v57, vcc
	global_load_dwordx2 v[24:25], v[24:25], off
	s_nop 0
	global_load_dwordx2 v[22:23], v[22:23], off
	v_cvt_f32_f16_sdwa v67, v50 dst_sel:DWORD dst_unused:UNUSED_PAD src0_sel:WORD_1
	global_load_dword v79, v[32:33], off
	v_cvt_f32_f16_e32 v66, v50
	v_cvt_f32_f16_sdwa v33, v52 dst_sel:DWORD dst_unused:UNUSED_PAD src0_sel:WORD_1
	v_cvt_f32_f16_e32 v32, v52
	v_cvt_f32_f16_sdwa v71, v53 dst_sel:DWORD dst_unused:UNUSED_PAD src0_sel:WORD_1
	v_cvt_f32_f16_e32 v70, v53
	s_waitcnt vmcnt(12)
	v_cvt_f32_f16_sdwa v75, v44 dst_sel:DWORD dst_unused:UNUSED_PAD src0_sel:WORD_1
	v_cvt_f32_f16_e32 v74, v44
	v_cvt_f32_f16_sdwa v53, v51 dst_sel:DWORD dst_unused:UNUSED_PAD src0_sel:WORD_1
	v_cvt_f32_f16_e32 v52, v51
	v_cvt_f32_f16_sdwa v93, v45 dst_sel:DWORD dst_unused:UNUSED_PAD src0_sel:WORD_1
	v_cvt_f32_f16_e32 v92, v45
	v_cvt_f32_f16_sdwa v65, v42 dst_sel:DWORD dst_unused:UNUSED_PAD src0_sel:WORD_1
	v_cvt_f32_f16_e32 v64, v42
	v_pk_add_f32 v[68:69], v[66:67], 1.0 op_sel_hi:[1,0] neg_lo:[1,0] neg_hi:[1,0]
	v_cvt_f32_f16_sdwa v73, v48 dst_sel:DWORD dst_unused:UNUSED_PAD src0_sel:WORD_1
	v_cvt_f32_f16_e32 v72, v48
	v_cvt_f32_f16_sdwa v83, v46 dst_sel:DWORD dst_unused:UNUSED_PAD src0_sel:WORD_1
	v_cvt_f32_f16_e32 v82, v46
	v_cvt_f32_f16_sdwa v67, v43 dst_sel:DWORD dst_unused:UNUSED_PAD src0_sel:WORD_1
	v_cvt_f32_f16_e32 v66, v43
	v_cvt_f32_f16_sdwa v89, v49 dst_sel:DWORD dst_unused:UNUSED_PAD src0_sel:WORD_1
	v_cvt_f32_f16_e32 v88, v49
	v_cvt_f32_f16_sdwa v91, v47 dst_sel:DWORD dst_unused:UNUSED_PAD src0_sel:WORD_1
	v_cvt_f32_f16_e32 v90, v47
	v_pk_add_f32 v[32:33], v[32:33], 1.0 op_sel_hi:[1,0] neg_lo:[1,0] neg_hi:[1,0]
	v_pk_add_f32 v[86:87], v[70:71], 1.0 op_sel_hi:[1,0] neg_lo:[1,0] neg_hi:[1,0]
	v_pk_mul_f32 v[84:85], v[32:33], v[74:75]
	v_pk_add_f32 v[70:71], v[52:53], 1.0 op_sel_hi:[1,0] neg_lo:[1,0] neg_hi:[1,0]
	v_pk_mul_f32 v[94:95], v[86:87], v[92:93]
	v_pk_mul_f32 v[50:51], v[68:69], v[84:85]
	v_pk_mul_f32 v[52:53], v[70:71], v[94:95]
	v_add_u32_e32 v80, v59, v62
	s_waitcnt lgkmcnt(0)
	s_barrier
	v_pk_mul_f32 v[42:43], v[68:69], v[72:73]
	v_pk_mul_f32 v[44:45], v[70:71], v[88:89]
	v_pk_mul_f32 v[46:47], v[68:69], v[82:83]
	v_pk_mul_f32 v[48:49], v[70:71], v[90:91]
	v_pk_mul_f32 v[68:69], v[68:69], v[32:33]
	v_pk_mul_f32 v[70:71], v[70:71], v[86:87]
	v_mov_b32_e32 v120, v64
	v_mov_b32_e32 v121, v46
	v_mov_b32_e32 v122, v65
	v_mov_b32_e32 v123, v47
	v_mov_b32_e32 v124, v42
	v_mov_b32_e32 v125, v50
	v_mov_b32_e32 v126, v43
	v_mov_b32_e32 v127, v51
	v_mov_b32_e32 v128, v66
	v_mov_b32_e32 v129, v48
	v_mov_b32_e32 v130, v67
	v_mov_b32_e32 v131, v49
	v_mov_b32_e32 v132, v44
	v_mov_b32_e32 v133, v52
	v_mov_b32_e32 v134, v45
	v_mov_b32_e32 v135, v53
	ds_write_b128 v80, v[120:123]
	ds_write_b128 v80, v[124:127] offset:256
	ds_write_b128 v80, v[128:131] offset:512
	ds_write_b128 v80, v[132:135] offset:768
	ds_write_b128 v80, v[68:71] offset:1024
	v_cvt_f32_f16_e32 v51, v38
	v_cvt_f32_f16_sdwa v53, v38 dst_sel:DWORD dst_unused:UNUSED_PAD src0_sel:WORD_1
	v_cvt_f32_f16_e32 v50, v40
	v_cvt_f32_f16_sdwa v52, v40 dst_sel:DWORD dst_unused:UNUSED_PAD src0_sel:WORD_1
	v_cvt_f32_f16_e32 v63, v39
	v_cvt_f32_f16_sdwa v65, v39 dst_sel:DWORD dst_unused:UNUSED_PAD src0_sel:WORD_1
	v_cvt_f32_f16_e32 v62, v41
	v_cvt_f32_f16_sdwa v64, v41 dst_sel:DWORD dst_unused:UNUSED_PAD src0_sel:WORD_1
	v_mov_b32_e32 v42, v51
	v_mov_b32_e32 v43, v53
	v_mov_b32_e32 v44, v50
	v_mov_b32_e32 v45, v52
	v_mov_b32_e32 v38, v63
	v_mov_b32_e32 v39, v65
	v_pk_mul_f32 v[42:43], v[32:33], v[42:43]
	v_pk_mul_f32 v[46:47], v[32:33], v[44:45]
	v_mov_b32_e32 v32, v83
	v_pk_mul_f32 v[44:45], v[86:87], v[38:39]
	v_mov_b32_e32 v38, v62
	v_mov_b32_e32 v39, v64
	v_pk_fma_f32 v[40:41], v[82:83], v[50:51], 0 op_sel_hi:[0,1,0]
	v_pk_mul_f32 v[48:49], v[86:87], v[38:39]
	ds_write_b128 v80, v[42:45] offset:1280
	ds_write_b128 v80, v[46:49] offset:1536
	v_pk_fma_f32 v[32:33], v[32:33], v[52:53], v[40:41] op_sel_hi:[0,1,1]
	v_mov_b32_e32 v40, v73
	v_pk_fma_f32 v[44:45], v[72:73], v[50:51], 0 op_sel_hi:[0,1,0]
	v_pk_fma_f32 v[40:41], v[40:41], v[52:53], v[44:45] op_sel_hi:[0,1,1]
	v_pk_fma_f32 v[44:45], v[84:85], v[50:51], 0 op_sel_hi:[0,1,0]
	v_pk_fma_f32 v[44:45], v[84:85], v[52:53], v[44:45] op_sel:[1,0,0]
	v_mov_b32_e32 v38, v91
	v_pk_fma_f32 v[32:33], v[90:91], v[62:63], v[32:33] op_sel_hi:[0,1,1]
	v_mov_b32_e32 v42, v89
	v_pk_fma_f32 v[40:41], v[88:89], v[62:63], v[40:41] op_sel_hi:[0,1,1]
	v_pk_fma_f32 v[44:45], v[94:95], v[62:63], v[44:45] op_sel_hi:[0,1,1]
	v_pk_fma_f32 v[32:33], v[38:39], v[64:65], v[32:33] op_sel_hi:[0,1,1]
	v_pk_fma_f32 v[40:41], v[42:43], v[64:65], v[40:41] op_sel_hi:[0,1,1]
	v_pk_fma_f32 v[44:45], v[94:95], v[64:65], v[44:45] op_sel:[1,0,0]
	v_cvt_f32_f16_e32 v49, v34
	v_cvt_f32_f16_sdwa v51, v34 dst_sel:DWORD dst_unused:UNUSED_PAD src0_sel:WORD_1
	v_cvt_f32_f16_e32 v63, v35
	v_cvt_f32_f16_sdwa v65, v35 dst_sel:DWORD dst_unused:UNUSED_PAD src0_sel:WORD_1
	v_cvt_f32_f16_e32 v48, v36
	v_cvt_f32_f16_sdwa v50, v36 dst_sel:DWORD dst_unused:UNUSED_PAD src0_sel:WORD_1
	v_cvt_f32_f16_e32 v62, v37
	v_cvt_f32_f16_sdwa v64, v37 dst_sel:DWORD dst_unused:UNUSED_PAD src0_sel:WORD_1
	v_mov_b32_e32 v34, v49
	v_mov_b32_e32 v35, v51
	v_mov_b32_e32 v36, v63
	v_mov_b32_e32 v37, v65
	ds_write_b128 v80, v[34:37] offset:1792
	v_mov_b32_e32 v34, v48
	v_mov_b32_e32 v35, v50
	v_mov_b32_e32 v36, v62
	v_mov_b32_e32 v37, v64
	v_mov_b32_e32 v52, v75
	ds_write_b128 v80, v[34:37] offset:2048
	v_pk_fma_f32 v[34:35], v[74:75], v[48:49], 0 op_sel_hi:[0,1,0]
	v_pk_fma_f32 v[34:35], v[52:53], v[50:51], v[34:35] op_sel_hi:[0,1,1]
	v_mov_b32_e32 v66, v93
	v_pk_fma_f32 v[34:35], v[92:93], v[62:63], v[34:35] op_sel_hi:[0,1,1]
	v_pk_fma_f32 v[34:35], v[66:67], v[64:65], v[34:35] op_sel_hi:[0,1,1]
	v_mov_b32_dpp v38, v32 row_ror:8 row_mask:0xf bank_mask:0xf bound_ctrl:1
	v_mov_b32_dpp v39, v33 row_ror:8 row_mask:0xf bank_mask:0xf bound_ctrl:1
	v_mov_b32_dpp v42, v40 row_ror:8 row_mask:0xf bank_mask:0xf bound_ctrl:1
	v_mov_b32_dpp v43, v41 row_ror:8 row_mask:0xf bank_mask:0xf bound_ctrl:1
	v_mov_b32_dpp v46, v44 row_ror:8 row_mask:0xf bank_mask:0xf bound_ctrl:1
	v_mov_b32_dpp v47, v45 row_ror:8 row_mask:0xf bank_mask:0xf bound_ctrl:1
	v_mov_b32_dpp v36, v34 row_ror:8 row_mask:0xf bank_mask:0xf bound_ctrl:1
	v_mov_b32_dpp v37, v35 row_ror:8 row_mask:0xf bank_mask:0xf bound_ctrl:1
	v_pk_add_f32 v[32:33], v[32:33], v[38:39]
	v_pk_add_f32 v[40:41], v[40:41], v[42:43]
	v_pk_add_f32 v[44:45], v[44:45], v[46:47]
	v_pk_add_f32 v[34:35], v[34:35], v[36:37]
	v_mov_b32_dpp v38, v32 row_ror:4 row_mask:0xf bank_mask:0xf bound_ctrl:1
	v_mov_b32_dpp v39, v33 row_ror:4 row_mask:0xf bank_mask:0xf bound_ctrl:1
	v_mov_b32_dpp v42, v40 row_ror:4 row_mask:0xf bank_mask:0xf bound_ctrl:1
	v_mov_b32_dpp v43, v41 row_ror:4 row_mask:0xf bank_mask:0xf bound_ctrl:1
	v_mov_b32_dpp v46, v44 row_ror:4 row_mask:0xf bank_mask:0xf bound_ctrl:1
	v_mov_b32_dpp v47, v45 row_ror:4 row_mask:0xf bank_mask:0xf bound_ctrl:1
	v_mov_b32_dpp v36, v34 row_ror:4 row_mask:0xf bank_mask:0xf bound_ctrl:1
	v_mov_b32_dpp v37, v35 row_ror:4 row_mask:0xf bank_mask:0xf bound_ctrl:1
	v_pk_add_f32 v[32:33], v[32:33], v[38:39]
	v_pk_add_f32 v[40:41], v[40:41], v[42:43]
	v_pk_add_f32 v[44:45], v[44:45], v[46:47]
	v_pk_add_f32 v[34:35], v[34:35], v[36:37]
	v_mov_b32_dpp v38, v32 row_ror:2 row_mask:0xf bank_mask:0xf bound_ctrl:1
	v_mov_b32_dpp v39, v33 row_ror:2 row_mask:0xf bank_mask:0xf bound_ctrl:1
	v_mov_b32_dpp v42, v40 row_ror:2 row_mask:0xf bank_mask:0xf bound_ctrl:1
	v_mov_b32_dpp v43, v41 row_ror:2 row_mask:0xf bank_mask:0xf bound_ctrl:1
	v_mov_b32_dpp v46, v44 row_ror:2 row_mask:0xf bank_mask:0xf bound_ctrl:1
	v_mov_b32_dpp v47, v45 row_ror:2 row_mask:0xf bank_mask:0xf bound_ctrl:1
	v_mov_b32_dpp v36, v34 row_ror:2 row_mask:0xf bank_mask:0xf bound_ctrl:1
	v_mov_b32_dpp v37, v35 row_ror:2 row_mask:0xf bank_mask:0xf bound_ctrl:1
	v_pk_add_f32 v[32:33], v[32:33], v[38:39]
	v_pk_add_f32 v[40:41], v[40:41], v[42:43]
	v_pk_add_f32 v[44:45], v[44:45], v[46:47]
	v_pk_add_f32 v[34:35], v[34:35], v[36:37]
	v_mov_b32_dpp v38, v32 row_ror:1 row_mask:0xf bank_mask:0xf bound_ctrl:1
	v_mov_b32_dpp v39, v33 row_ror:1 row_mask:0xf bank_mask:0xf bound_ctrl:1
	v_mov_b32_dpp v42, v40 row_ror:1 row_mask:0xf bank_mask:0xf bound_ctrl:1
	v_mov_b32_dpp v43, v41 row_ror:1 row_mask:0xf bank_mask:0xf bound_ctrl:1
	v_mov_b32_dpp v46, v44 row_ror:1 row_mask:0xf bank_mask:0xf bound_ctrl:1
	v_mov_b32_dpp v47, v45 row_ror:1 row_mask:0xf bank_mask:0xf bound_ctrl:1
	v_mov_b32_dpp v36, v34 row_ror:1 row_mask:0xf bank_mask:0xf bound_ctrl:1
	v_mov_b32_dpp v37, v35 row_ror:1 row_mask:0xf bank_mask:0xf bound_ctrl:1
	s_and_saveexec_b64 s[20:21], s[0:1]
	s_cbranch_execz .LBB0_663
	v_pk_add_f32 v[38:39], v[32:33], v[38:39]
	v_pk_add_f32 v[32:33], v[40:41], v[42:43]
	s_mov_b32 s10, 0x3d800000
	v_pk_mul_f32 v[40:41], v[32:33], s[10:11] op_sel_hi:[1,0]
	v_pk_add_f32 v[32:33], v[44:45], v[46:47]
	v_pk_add_f32 v[34:35], v[34:35], v[36:37]
	v_pk_mul_f32 v[32:33], v[32:33], s[10:11] op_sel_hi:[1,0]
	v_pk_mul_f32 v[34:35], v[34:35], s[10:11] op_sel_hi:[1,0]
	ds_write_b128 v77, v[38:41] offset:36864
	ds_write_b128 v77, v[32:35] offset:36880

.LBB0_665:
	s_waitcnt vmcnt(11)
	v_cvt_f32_f16_sdwa v59, v8 dst_sel:DWORD dst_unused:UNUSED_PAD src0_sel:WORD_1
	v_cvt_f32_f16_e32 v58, v8
	s_waitcnt vmcnt(10)
	v_cvt_f32_f16_sdwa v57, v16 dst_sel:DWORD dst_unused:UNUSED_PAD src0_sel:WORD_1
	v_cvt_f32_f16_e32 v56, v16
	v_cvt_f32_f16_sdwa v61, v9 dst_sel:DWORD dst_unused:UNUSED_PAD src0_sel:WORD_1
	v_pk_add_f32 v[70:71], v[58:59], 1.0 op_sel_hi:[1,0] neg_lo:[1,0] neg_hi:[1,0]
	v_cvt_f32_f16_sdwa v59, v17 dst_sel:DWORD dst_unused:UNUSED_PAD src0_sel:WORD_1
	v_cvt_f32_f16_e32 v58, v17
	v_cvt_f32_f16_e32 v60, v9
	s_waitcnt vmcnt(9)
	v_cvt_f32_f16_sdwa v87, v18 dst_sel:DWORD dst_unused:UNUSED_PAD src0_sel:WORD_1
	v_cvt_f32_f16_e32 v86, v18
	s_waitcnt vmcnt(3)
	v_cvt_f32_f16_sdwa v89, v24 dst_sel:DWORD dst_unused:UNUSED_PAD src0_sel:WORD_1
	v_cvt_f32_f16_e32 v88, v24
	v_cvt_f32_f16_sdwa v97, v25 dst_sel:DWORD dst_unused:UNUSED_PAD src0_sel:WORD_1
	v_cvt_f32_f16_e32 v96, v25
	v_cvt_f32_f16_sdwa v99, v19 dst_sel:DWORD dst_unused:UNUSED_PAD src0_sel:WORD_1
	v_cvt_f32_f16_e32 v98, v19
	v_cvt_f32_f16_sdwa v55, v12 dst_sel:DWORD dst_unused:UNUSED_PAD src0_sel:WORD_1
	v_cvt_f32_f16_e32 v54, v12
	v_pk_add_f32 v[74:75], v[56:57], 1.0 op_sel_hi:[1,0] neg_lo:[1,0] neg_hi:[1,0]
	v_cvt_f32_f16_sdwa v85, v6 dst_sel:DWORD dst_unused:UNUSED_PAD src0_sel:WORD_1
	v_cvt_f32_f16_e32 v84, v6
	v_cvt_f32_f16_sdwa v57, v13 dst_sel:DWORD dst_unused:UNUSED_PAD src0_sel:WORD_1
	v_cvt_f32_f16_e32 v56, v13
	v_cvt_f32_f16_sdwa v95, v7 dst_sel:DWORD dst_unused:UNUSED_PAD src0_sel:WORD_1
	v_cvt_f32_f16_e32 v94, v7
	v_pk_add_f32 v[92:93], v[58:59], 1.0 op_sel_hi:[1,0] neg_lo:[1,0] neg_hi:[1,0]
	v_pk_add_f32 v[72:73], v[60:61], 1.0 op_sel_hi:[1,0] neg_lo:[1,0] neg_hi:[1,0]
	v_pk_mul_f32 v[90:91], v[74:75], v[86:87]
	v_pk_mul_f32 v[62:63], v[70:71], v[88:89]
	v_pk_mul_f32 v[64:65], v[72:73], v[96:97]
	v_pk_mul_f32 v[100:101], v[92:93], v[98:99]
	v_pk_mul_f32 v[58:59], v[70:71], v[84:85]
	v_pk_mul_f32 v[60:61], v[72:73], v[94:95]
	v_pk_mul_f32 v[66:67], v[70:71], v[90:91]
	v_pk_mul_f32 v[68:69], v[72:73], v[100:101]
	v_pk_mul_f32 v[70:71], v[70:71], v[74:75]
	v_pk_mul_f32 v[72:73], v[72:73], v[92:93]
	v_mov_b32_e32 v120, v54
	v_mov_b32_e32 v121, v62
	v_mov_b32_e32 v122, v55
	v_mov_b32_e32 v123, v63
	v_mov_b32_e32 v124, v58
	v_mov_b32_e32 v125, v66
	v_mov_b32_e32 v126, v59
	v_mov_b32_e32 v127, v67
	v_mov_b32_e32 v128, v56
	v_mov_b32_e32 v129, v64
	v_mov_b32_e32 v130, v57
	v_mov_b32_e32 v131, v65
	v_mov_b32_e32 v132, v60
	v_mov_b32_e32 v133, v68
	v_mov_b32_e32 v134, v61
	v_mov_b32_e32 v135, v69
	ds_write_b128 v76, v[120:123]
	ds_write_b128 v76, v[124:127] offset:256
	ds_write_b128 v76, v[128:131] offset:512
	ds_write_b128 v76, v[132:135] offset:768
	ds_write_b128 v76, v[70:73] offset:1024
	v_cvt_f32_f16_e32 v62, v14
	v_cvt_f32_f16_sdwa v64, v14 dst_sel:DWORD dst_unused:UNUSED_PAD src0_sel:WORD_1
	v_cvt_f32_f16_e32 v63, v10
	v_cvt_f32_f16_sdwa v65, v10 dst_sel:DWORD dst_unused:UNUSED_PAD src0_sel:WORD_1
	v_cvt_f32_f16_e32 v69, v11
	v_cvt_f32_f16_sdwa v71, v11 dst_sel:DWORD dst_unused:UNUSED_PAD src0_sel:WORD_1
	v_cvt_f32_f16_e32 v68, v15
	v_cvt_f32_f16_sdwa v70, v15 dst_sel:DWORD dst_unused:UNUSED_PAD src0_sel:WORD_1
	v_mov_b32_e32 v56, v62
	v_mov_b32_e32 v57, v64
	v_mov_b32_e32 v54, v63
	v_mov_b32_e32 v55, v65
	v_pk_mul_f32 v[58:59], v[74:75], v[56:57]
	v_mov_b32_e32 v56, v69
	v_mov_b32_e32 v57, v71
	v_pk_mul_f32 v[54:55], v[74:75], v[54:55]
	v_pk_mul_f32 v[56:57], v[92:93], v[56:57]
	v_mov_b32_e32 v60, v68
	v_mov_b32_e32 v61, v70
	v_mov_b32_e32 v66, v89
	v_pk_mul_f32 v[60:61], v[92:93], v[60:61]
	ds_write_b128 v76, v[54:57] offset:1280
	ds_write_b128 v76, v[58:61] offset:1536
	v_pk_fma_f32 v[54:55], v[88:89], v[62:63], 0 op_sel_hi:[0,1,0]
	v_pk_fma_f32 v[54:55], v[66:67], v[64:65], v[54:55] op_sel_hi:[0,1,1]
	v_mov_b32_e32 v58, v85
	v_pk_fma_f32 v[66:67], v[84:85], v[62:63], 0 op_sel_hi:[0,1,0]
	v_pk_fma_f32 v[62:63], v[90:91], v[62:63], 0 op_sel_hi:[0,1,0]
	v_pk_fma_f32 v[58:59], v[58:59], v[64:65], v[66:67] op_sel_hi:[0,1,1]
	v_pk_fma_f32 v[62:63], v[90:91], v[64:65], v[62:63] op_sel:[1,0,0]
	v_mov_b32_e32 v72, v97
	v_pk_fma_f32 v[54:55], v[96:97], v[68:69], v[54:55] op_sel_hi:[0,1,1]
	v_mov_b32_e32 v60, v95
	v_pk_fma_f32 v[58:59], v[94:95], v[68:69], v[58:59] op_sel_hi:[0,1,1]
	v_pk_fma_f32 v[62:63], v[100:101], v[68:69], v[62:63] op_sel_hi:[0,1,1]
	v_pk_fma_f32 v[54:55], v[72:73], v[70:71], v[54:55] op_sel_hi:[0,1,1]
	v_pk_fma_f32 v[58:59], v[60:61], v[70:71], v[58:59] op_sel_hi:[0,1,1]
	v_pk_fma_f32 v[62:63], v[100:101], v[70:71], v[62:63] op_sel:[1,0,0]
	v_cvt_f32_f16_e32 v71, v20
	v_cvt_f32_f16_sdwa v73, v20 dst_sel:DWORD dst_unused:UNUSED_PAD src0_sel:WORD_1
	v_cvt_f32_f16_e32 v85, v21
	v_cvt_f32_f16_sdwa v89, v21 dst_sel:DWORD dst_unused:UNUSED_PAD src0_sel:WORD_1
	s_waitcnt vmcnt(13)
	v_cvt_f32_f16_e32 v70, v22
	v_cvt_f32_f16_sdwa v72, v22 dst_sel:DWORD dst_unused:UNUSED_PAD src0_sel:WORD_1
	v_cvt_f32_f16_e32 v84, v23
	v_cvt_f32_f16_sdwa v88, v23 dst_sel:DWORD dst_unused:UNUSED_PAD src0_sel:WORD_1
	v_mov_b32_e32 v66, v71
	v_mov_b32_e32 v67, v73
	v_mov_b32_e32 v68, v85
	v_mov_b32_e32 v69, v89
	ds_write_b128 v76, v[66:69] offset:1792
	v_mov_b32_e32 v66, v70
	v_mov_b32_e32 v67, v72
	v_mov_b32_e32 v68, v84
	v_mov_b32_e32 v69, v88
	v_mov_b32_e32 v74, v87
	ds_write_b128 v76, v[66:69] offset:2048
	v_pk_fma_f32 v[66:67], v[86:87], v[70:71], 0 op_sel_hi:[0,1,0]
	v_pk_fma_f32 v[66:67], v[74:75], v[72:73], v[66:67] op_sel_hi:[0,1,1]
	v_mov_b32_e32 v90, v99
	v_pk_fma_f32 v[66:67], v[98:99], v[84:85], v[66:67] op_sel_hi:[0,1,1]
	v_pk_fma_f32 v[66:67], v[90:91], v[88:89], v[66:67] op_sel_hi:[0,1,1]
	v_mov_b32_dpp v56, v54 row_ror:8 row_mask:0xf bank_mask:0xf bound_ctrl:1
	v_mov_b32_dpp v57, v55 row_ror:8 row_mask:0xf bank_mask:0xf bound_ctrl:1
	v_mov_b32_dpp v60, v58 row_ror:8 row_mask:0xf bank_mask:0xf bound_ctrl:1
	v_mov_b32_dpp v61, v59 row_ror:8 row_mask:0xf bank_mask:0xf bound_ctrl:1
	v_mov_b32_dpp v64, v62 row_ror:8 row_mask:0xf bank_mask:0xf bound_ctrl:1
	v_mov_b32_dpp v65, v63 row_ror:8 row_mask:0xf bank_mask:0xf bound_ctrl:1
	v_mov_b32_dpp v68, v66 row_ror:8 row_mask:0xf bank_mask:0xf bound_ctrl:1
	v_mov_b32_dpp v69, v67 row_ror:8 row_mask:0xf bank_mask:0xf bound_ctrl:1
	v_pk_add_f32 v[54:55], v[54:55], v[56:57]
	v_pk_add_f32 v[58:59], v[58:59], v[60:61]
	v_pk_add_f32 v[62:63], v[62:63], v[64:65]
	v_pk_add_f32 v[66:67], v[66:67], v[68:69]
	v_mov_b32_dpp v56, v54 row_ror:4 row_mask:0xf bank_mask:0xf bound_ctrl:1
	v_mov_b32_dpp v57, v55 row_ror:4 row_mask:0xf bank_mask:0xf bound_ctrl:1
	v_mov_b32_dpp v60, v58 row_ror:4 row_mask:0xf bank_mask:0xf bound_ctrl:1
	v_mov_b32_dpp v61, v59 row_ror:4 row_mask:0xf bank_mask:0xf bound_ctrl:1
	v_mov_b32_dpp v64, v62 row_ror:4 row_mask:0xf bank_mask:0xf bound_ctrl:1
	v_mov_b32_dpp v65, v63 row_ror:4 row_mask:0xf bank_mask:0xf bound_ctrl:1
	v_mov_b32_dpp v68, v66 row_ror:4 row_mask:0xf bank_mask:0xf bound_ctrl:1
	v_mov_b32_dpp v69, v67 row_ror:4 row_mask:0xf bank_mask:0xf bound_ctrl:1
	v_pk_add_f32 v[54:55], v[54:55], v[56:57]
	v_pk_add_f32 v[58:59], v[58:59], v[60:61]
	v_pk_add_f32 v[62:63], v[62:63], v[64:65]
	v_pk_add_f32 v[66:67], v[66:67], v[68:69]
	v_mov_b32_dpp v56, v54 row_ror:2 row_mask:0xf bank_mask:0xf bound_ctrl:1
	v_mov_b32_dpp v57, v55 row_ror:2 row_mask:0xf bank_mask:0xf bound_ctrl:1
	v_mov_b32_dpp v60, v58 row_ror:2 row_mask:0xf bank_mask:0xf bound_ctrl:1
	v_mov_b32_dpp v61, v59 row_ror:2 row_mask:0xf bank_mask:0xf bound_ctrl:1
	v_mov_b32_dpp v64, v62 row_ror:2 row_mask:0xf bank_mask:0xf bound_ctrl:1
	v_mov_b32_dpp v65, v63 row_ror:2 row_mask:0xf bank_mask:0xf bound_ctrl:1
	v_mov_b32_dpp v68, v66 row_ror:2 row_mask:0xf bank_mask:0xf bound_ctrl:1
	v_mov_b32_dpp v69, v67 row_ror:2 row_mask:0xf bank_mask:0xf bound_ctrl:1
	v_pk_add_f32 v[54:55], v[54:55], v[56:57]
	v_pk_add_f32 v[58:59], v[58:59], v[60:61]
	v_pk_add_f32 v[62:63], v[62:63], v[64:65]
	v_pk_add_f32 v[66:67], v[66:67], v[68:69]
	v_mov_b32_dpp v56, v54 row_ror:1 row_mask:0xf bank_mask:0xf bound_ctrl:1
	v_mov_b32_dpp v57, v55 row_ror:1 row_mask:0xf bank_mask:0xf bound_ctrl:1
	v_mov_b32_dpp v60, v58 row_ror:1 row_mask:0xf bank_mask:0xf bound_ctrl:1
	v_mov_b32_dpp v61, v59 row_ror:1 row_mask:0xf bank_mask:0xf bound_ctrl:1
	v_mov_b32_dpp v64, v62 row_ror:1 row_mask:0xf bank_mask:0xf bound_ctrl:1
	v_mov_b32_dpp v65, v63 row_ror:1 row_mask:0xf bank_mask:0xf bound_ctrl:1
	v_mov_b32_dpp v68, v66 row_ror:1 row_mask:0xf bank_mask:0xf bound_ctrl:1
	v_mov_b32_dpp v69, v67 row_ror:1 row_mask:0xf bank_mask:0xf bound_ctrl:1
	s_and_saveexec_b64 s[16:17], s[0:1]
	s_cbranch_execz .LBB0_667
	v_pk_add_f32 v[54:55], v[54:55], v[56:57]
	v_pk_add_f32 v[56:57], v[58:59], v[60:61]
	v_add_u32_e32 v58, 0x1ab00, v77
	v_pk_mul_f32 v[56:57], v[56:57], s[12:13] op_sel_hi:[1,0]
	ds_write_b128 v58, v[54:57]
	v_pk_add_f32 v[54:55], v[62:63], v[64:65]
	v_pk_add_f32 v[56:57], v[66:67], v[68:69]
	v_pk_mul_f32 v[54:55], v[54:55], s[12:13] op_sel_hi:[1,0]
	v_pk_mul_f32 v[56:57], v[56:57], s[12:13] op_sel_hi:[1,0]
	ds_write_b128 v58, v[54:57] offset:16

.LBB0_669:
	ds_read_b128 v[120:123], v168 offset:39680
	ds_read_b128 v[124:127], v169 offset:39680
	ds_read_b128 v[128:131], v170 offset:39680
	ds_read_b128 v[132:135], v171 offset:39680
	ds_read_b128 v[136:139], v172 offset:39680
	ds_read_b128 v[140:143], v173 offset:39680
	ds_read_b128 v[144:147], v174 offset:39680
	ds_read_b128 v[148:151], v175 offset:39680
	s_cmpk_gt_u32 s13, 0x1fd
	s_cselect_b64 s[16:17], -1, 0
	s_nop 0
	s_nop 0
	s_nop 0
	s_waitcnt lgkmcnt(0)
	v_pk_add_f32 v[120:121], v[120:121], v[124:125]
	v_pk_add_f32 v[122:123], v[122:123], v[126:127]
	v_pk_add_f32 v[128:129], v[128:129], v[132:133]
	v_pk_add_f32 v[130:131], v[130:131], v[134:135]
	v_pk_add_f32 v[120:121], v[120:121], v[128:129]
	v_pk_add_f32 v[122:123], v[122:123], v[130:131]
	v_pk_add_f32 v[120:121], v[120:121], v[122:123]
	v_add_f32_e32 v120, v120, v121
	v_pk_add_f32 v[136:137], v[136:137], v[140:141]
	v_pk_add_f32 v[138:139], v[138:139], v[142:143]
	v_pk_add_f32 v[144:145], v[144:145], v[148:149]
	v_pk_add_f32 v[146:147], v[146:147], v[150:151]
	v_pk_add_f32 v[136:137], v[136:137], v[144:145]
	v_pk_add_f32 v[138:139], v[138:139], v[146:147]
	v_pk_add_f32 v[136:137], v[136:137], v[138:139]
	v_add_f32_e32 v136, v136, v137
	v_bfi_b32 v61, v176, v136, v120
	v_bfi_b32 v60, v176, v120, v136
	v_and_b32_sdwa v62, v61, v82 dst_sel:DWORD dst_unused:UNUSED_PAD src0_sel:WORD_1 src1_sel:DWORD
	v_and_b32_sdwa v63, v60, v82 dst_sel:DWORD dst_unused:UNUSED_PAD src0_sel:WORD_1 src1_sel:DWORD
	v_add3_u32 v61, v61, v62, s7
	v_add3_u32 v60, v60, v63, s7
	v_lshrrev_b32_e32 v61, 16, v61
	v_and_or_b32 v62, v60, s9, v61
	v_add_co_u32_e32 v60, vcc, 0xfffe0000, v48
	s_nop 1
	v_addc_co_u32_e32 v61, vcc, -1, v49, vcc
	s_and_b64 vcc, exec, s[16:17]
	global_store_dword v[60:61], v62, off
	s_barrier
	s_cbranch_vccnz .LBB0_673
	s_waitcnt vmcnt(11)
	v_cvt_f32_f16_sdwa v65, v30 dst_sel:DWORD dst_unused:UNUSED_PAD src0_sel:WORD_1
	v_cvt_f32_f16_e32 v64, v30
	s_waitcnt vmcnt(6)
	v_cvt_f32_f16_sdwa v63, v38 dst_sel:DWORD dst_unused:UNUSED_PAD src0_sel:WORD_1
	v_cvt_f32_f16_e32 v62, v38
	v_cvt_f32_f16_sdwa v67, v31 dst_sel:DWORD dst_unused:UNUSED_PAD src0_sel:WORD_1
	v_pk_add_f32 v[84:85], v[64:65], 1.0 op_sel_hi:[1,0] neg_lo:[1,0] neg_hi:[1,0]
	v_cvt_f32_f16_sdwa v65, v39 dst_sel:DWORD dst_unused:UNUSED_PAD src0_sel:WORD_1
	v_cvt_f32_f16_e32 v64, v39
	v_cvt_f32_f16_e32 v66, v31
	v_cvt_f32_f16_sdwa v93, v40 dst_sel:DWORD dst_unused:UNUSED_PAD src0_sel:WORD_1
	v_cvt_f32_f16_e32 v92, v40
	s_waitcnt vmcnt(4)
	v_cvt_f32_f16_sdwa v95, v46 dst_sel:DWORD dst_unused:UNUSED_PAD src0_sel:WORD_1
	v_cvt_f32_f16_e32 v94, v46
	v_cvt_f32_f16_sdwa v103, v47 dst_sel:DWORD dst_unused:UNUSED_PAD src0_sel:WORD_1
	v_cvt_f32_f16_e32 v102, v47
	v_cvt_f32_f16_sdwa v105, v41 dst_sel:DWORD dst_unused:UNUSED_PAD src0_sel:WORD_1
	v_cvt_f32_f16_e32 v104, v41
	v_cvt_f32_f16_sdwa v61, v34 dst_sel:DWORD dst_unused:UNUSED_PAD src0_sel:WORD_1
	v_cvt_f32_f16_e32 v60, v34
	v_pk_add_f32 v[88:89], v[62:63], 1.0 op_sel_hi:[1,0] neg_lo:[1,0] neg_hi:[1,0]
	v_cvt_f32_f16_sdwa v91, v28 dst_sel:DWORD dst_unused:UNUSED_PAD src0_sel:WORD_1
	v_cvt_f32_f16_e32 v90, v28
	v_cvt_f32_f16_sdwa v63, v35 dst_sel:DWORD dst_unused:UNUSED_PAD src0_sel:WORD_1
	v_cvt_f32_f16_e32 v62, v35
	v_cvt_f32_f16_sdwa v101, v29 dst_sel:DWORD dst_unused:UNUSED_PAD src0_sel:WORD_1
	v_cvt_f32_f16_e32 v100, v29
	v_pk_add_f32 v[98:99], v[64:65], 1.0 op_sel_hi:[1,0] neg_lo:[1,0] neg_hi:[1,0]
	v_pk_add_f32 v[86:87], v[66:67], 1.0 op_sel_hi:[1,0] neg_lo:[1,0] neg_hi:[1,0]
	v_pk_mul_f32 v[96:97], v[88:89], v[92:93]
	v_pk_mul_f32 v[68:69], v[84:85], v[94:95]
	v_pk_mul_f32 v[70:71], v[86:87], v[102:103]
	v_pk_mul_f32 v[106:107], v[98:99], v[104:105]
	v_pk_mul_f32 v[64:65], v[84:85], v[90:91]
	v_pk_mul_f32 v[66:67], v[86:87], v[100:101]
	v_pk_mul_f32 v[72:73], v[84:85], v[96:97]
	v_pk_mul_f32 v[74:75], v[86:87], v[106:107]
	v_pk_mul_f32 v[84:85], v[84:85], v[88:89]
	v_pk_mul_f32 v[86:87], v[86:87], v[98:99]
	v_mov_b32_e32 v120, v60
	v_mov_b32_e32 v121, v68
	v_mov_b32_e32 v122, v61
	v_mov_b32_e32 v123, v69
	v_mov_b32_e32 v124, v64
	v_mov_b32_e32 v125, v72
	v_mov_b32_e32 v126, v65
	v_mov_b32_e32 v127, v73
	v_mov_b32_e32 v128, v62
	v_mov_b32_e32 v129, v70
	v_mov_b32_e32 v130, v63
	v_mov_b32_e32 v131, v71
	v_mov_b32_e32 v132, v66
	v_mov_b32_e32 v133, v74
	v_mov_b32_e32 v134, v67
	v_mov_b32_e32 v135, v75
	ds_write_b128 v80, v[120:123]
	ds_write_b128 v80, v[124:127] offset:256
	ds_write_b128 v80, v[128:131] offset:512
	ds_write_b128 v80, v[132:135] offset:768
	ds_write_b128 v80, v[84:87] offset:1024
	v_cvt_f32_f16_e32 v68, v36
	v_cvt_f32_f16_sdwa v70, v36 dst_sel:DWORD dst_unused:UNUSED_PAD src0_sel:WORD_1
	v_cvt_f32_f16_e32 v69, v32
	v_cvt_f32_f16_sdwa v71, v32 dst_sel:DWORD dst_unused:UNUSED_PAD src0_sel:WORD_1
	v_cvt_f32_f16_e32 v75, v33
	v_cvt_f32_f16_sdwa v85, v33 dst_sel:DWORD dst_unused:UNUSED_PAD src0_sel:WORD_1
	v_cvt_f32_f16_e32 v74, v37
	v_cvt_f32_f16_sdwa v84, v37 dst_sel:DWORD dst_unused:UNUSED_PAD src0_sel:WORD_1
	v_mov_b32_e32 v62, v68
	v_mov_b32_e32 v63, v70
	v_mov_b32_e32 v60, v69
	v_mov_b32_e32 v61, v71
	v_pk_mul_f32 v[64:65], v[88:89], v[62:63]
	v_mov_b32_e32 v62, v75
	v_mov_b32_e32 v63, v85
	v_pk_mul_f32 v[60:61], v[88:89], v[60:61]
	v_pk_mul_f32 v[62:63], v[98:99], v[62:63]
	v_mov_b32_e32 v66, v74
	v_mov_b32_e32 v67, v84
	v_mov_b32_e32 v72, v95
	v_pk_mul_f32 v[66:67], v[98:99], v[66:67]
	ds_write_b128 v80, v[60:63] offset:1280
	ds_write_b128 v80, v[64:67] offset:1536
	v_pk_fma_f32 v[60:61], v[94:95], v[68:69], 0 op_sel_hi:[0,1,0]
	v_pk_fma_f32 v[60:61], v[72:73], v[70:71], v[60:61] op_sel_hi:[0,1,1]
	v_mov_b32_e32 v64, v91
	v_pk_fma_f32 v[72:73], v[90:91], v[68:69], 0 op_sel_hi:[0,1,0]
	v_pk_fma_f32 v[68:69], v[96:97], v[68:69], 0 op_sel_hi:[0,1,0]
	v_pk_fma_f32 v[64:65], v[64:65], v[70:71], v[72:73] op_sel_hi:[0,1,1]
	v_pk_fma_f32 v[68:69], v[96:97], v[70:71], v[68:69] op_sel:[1,0,0]
	v_mov_b32_e32 v86, v103
	v_pk_fma_f32 v[60:61], v[102:103], v[74:75], v[60:61] op_sel_hi:[0,1,1]
	v_mov_b32_e32 v66, v101
	v_pk_fma_f32 v[64:65], v[100:101], v[74:75], v[64:65] op_sel_hi:[0,1,1]
	v_pk_fma_f32 v[68:69], v[106:107], v[74:75], v[68:69] op_sel_hi:[0,1,1]
	v_pk_fma_f32 v[60:61], v[86:87], v[84:85], v[60:61] op_sel_hi:[0,1,1]
	v_pk_fma_f32 v[64:65], v[66:67], v[84:85], v[64:65] op_sel_hi:[0,1,1]
	v_pk_fma_f32 v[68:69], v[106:107], v[84:85], v[68:69] op_sel:[1,0,0]
	v_cvt_f32_f16_e32 v85, v42
	v_cvt_f32_f16_sdwa v87, v42 dst_sel:DWORD dst_unused:UNUSED_PAD src0_sel:WORD_1
	v_cvt_f32_f16_e32 v91, v43
	v_cvt_f32_f16_sdwa v95, v43 dst_sel:DWORD dst_unused:UNUSED_PAD src0_sel:WORD_1
	s_waitcnt vmcnt(3)
	v_cvt_f32_f16_e32 v84, v44
	v_cvt_f32_f16_sdwa v86, v44 dst_sel:DWORD dst_unused:UNUSED_PAD src0_sel:WORD_1
	v_cvt_f32_f16_e32 v90, v45
	v_cvt_f32_f16_sdwa v94, v45 dst_sel:DWORD dst_unused:UNUSED_PAD src0_sel:WORD_1
	v_mov_b32_e32 v72, v85
	v_mov_b32_e32 v73, v87
	v_mov_b32_e32 v74, v91
	v_mov_b32_e32 v75, v95
	ds_write_b128 v80, v[72:75] offset:1792
	v_mov_b32_e32 v72, v84
	v_mov_b32_e32 v73, v86
	v_mov_b32_e32 v74, v90
	v_mov_b32_e32 v75, v94
	v_mov_b32_e32 v88, v93
	ds_write_b128 v80, v[72:75] offset:2048
	v_pk_fma_f32 v[72:73], v[92:93], v[84:85], 0 op_sel_hi:[0,1,0]
	v_pk_fma_f32 v[72:73], v[88:89], v[86:87], v[72:73] op_sel_hi:[0,1,1]
	v_mov_b32_e32 v96, v105
	v_pk_fma_f32 v[72:73], v[104:105], v[90:91], v[72:73] op_sel_hi:[0,1,1]
	v_pk_fma_f32 v[72:73], v[96:97], v[94:95], v[72:73] op_sel_hi:[0,1,1]
	v_mov_b32_dpp v62, v60 row_ror:8 row_mask:0xf bank_mask:0xf bound_ctrl:1
	v_mov_b32_dpp v63, v61 row_ror:8 row_mask:0xf bank_mask:0xf bound_ctrl:1
	v_mov_b32_dpp v66, v64 row_ror:8 row_mask:0xf bank_mask:0xf bound_ctrl:1
	v_mov_b32_dpp v67, v65 row_ror:8 row_mask:0xf bank_mask:0xf bound_ctrl:1
	v_mov_b32_dpp v70, v68 row_ror:8 row_mask:0xf bank_mask:0xf bound_ctrl:1
	v_mov_b32_dpp v71, v69 row_ror:8 row_mask:0xf bank_mask:0xf bound_ctrl:1
	v_mov_b32_dpp v74, v72 row_ror:8 row_mask:0xf bank_mask:0xf bound_ctrl:1
	v_mov_b32_dpp v75, v73 row_ror:8 row_mask:0xf bank_mask:0xf bound_ctrl:1
	v_pk_add_f32 v[60:61], v[60:61], v[62:63]
	v_pk_add_f32 v[64:65], v[64:65], v[66:67]
	v_pk_add_f32 v[68:69], v[68:69], v[70:71]
	v_pk_add_f32 v[72:73], v[72:73], v[74:75]
	v_mov_b32_dpp v62, v60 row_ror:4 row_mask:0xf bank_mask:0xf bound_ctrl:1
	v_mov_b32_dpp v63, v61 row_ror:4 row_mask:0xf bank_mask:0xf bound_ctrl:1
	v_mov_b32_dpp v66, v64 row_ror:4 row_mask:0xf bank_mask:0xf bound_ctrl:1
	v_mov_b32_dpp v67, v65 row_ror:4 row_mask:0xf bank_mask:0xf bound_ctrl:1
	v_mov_b32_dpp v70, v68 row_ror:4 row_mask:0xf bank_mask:0xf bound_ctrl:1
	v_mov_b32_dpp v71, v69 row_ror:4 row_mask:0xf bank_mask:0xf bound_ctrl:1
	v_mov_b32_dpp v74, v72 row_ror:4 row_mask:0xf bank_mask:0xf bound_ctrl:1
	v_mov_b32_dpp v75, v73 row_ror:4 row_mask:0xf bank_mask:0xf bound_ctrl:1
	v_pk_add_f32 v[60:61], v[60:61], v[62:63]
	v_pk_add_f32 v[64:65], v[64:65], v[66:67]
	v_pk_add_f32 v[68:69], v[68:69], v[70:71]
	v_pk_add_f32 v[72:73], v[72:73], v[74:75]
	v_mov_b32_dpp v62, v60 row_ror:2 row_mask:0xf bank_mask:0xf bound_ctrl:1
	v_mov_b32_dpp v63, v61 row_ror:2 row_mask:0xf bank_mask:0xf bound_ctrl:1
	v_mov_b32_dpp v66, v64 row_ror:2 row_mask:0xf bank_mask:0xf bound_ctrl:1
	v_mov_b32_dpp v67, v65 row_ror:2 row_mask:0xf bank_mask:0xf bound_ctrl:1
	v_mov_b32_dpp v70, v68 row_ror:2 row_mask:0xf bank_mask:0xf bound_ctrl:1
	v_mov_b32_dpp v71, v69 row_ror:2 row_mask:0xf bank_mask:0xf bound_ctrl:1
	v_mov_b32_dpp v74, v72 row_ror:2 row_mask:0xf bank_mask:0xf bound_ctrl:1
	v_mov_b32_dpp v75, v73 row_ror:2 row_mask:0xf bank_mask:0xf bound_ctrl:1
	v_pk_add_f32 v[60:61], v[60:61], v[62:63]
	v_pk_add_f32 v[64:65], v[64:65], v[66:67]
	v_pk_add_f32 v[68:69], v[68:69], v[70:71]
	v_pk_add_f32 v[72:73], v[72:73], v[74:75]
	v_mov_b32_dpp v62, v60 row_ror:1 row_mask:0xf bank_mask:0xf bound_ctrl:1
	v_mov_b32_dpp v63, v61 row_ror:1 row_mask:0xf bank_mask:0xf bound_ctrl:1
	v_mov_b32_dpp v66, v64 row_ror:1 row_mask:0xf bank_mask:0xf bound_ctrl:1
	v_mov_b32_dpp v67, v65 row_ror:1 row_mask:0xf bank_mask:0xf bound_ctrl:1
	v_mov_b32_dpp v70, v68 row_ror:1 row_mask:0xf bank_mask:0xf bound_ctrl:1
	v_mov_b32_dpp v71, v69 row_ror:1 row_mask:0xf bank_mask:0xf bound_ctrl:1
	v_mov_b32_dpp v74, v72 row_ror:1 row_mask:0xf bank_mask:0xf bound_ctrl:1
	v_mov_b32_dpp v75, v73 row_ror:1 row_mask:0xf bank_mask:0xf bound_ctrl:1
	s_and_saveexec_b64 s[18:19], s[0:1]
	s_cbranch_execz .LBB0_672
	v_pk_add_f32 v[60:61], v[60:61], v[62:63]
	v_pk_add_f32 v[62:63], v[64:65], v[66:67]
	s_nop 0
	v_pk_mul_f32 v[62:63], v[62:63], s[12:13] op_sel_hi:[1,0]
	ds_write_b128 v77, v[60:63] offset:36864
	v_pk_add_f32 v[60:61], v[68:69], v[70:71]
	v_pk_add_f32 v[62:63], v[72:73], v[74:75]
	v_pk_mul_f32 v[60:61], v[60:61], s[12:13] op_sel_hi:[1,0]
	v_pk_mul_f32 v[62:63], v[62:63], s[12:13] op_sel_hi:[1,0]
	ds_write_b128 v77, v[60:63] offset:36880
